# hand-off: setprio1 before barrier, drop dup lgkmcnt wait, setprio0 after barrier, all 6 GEMM K-loops
# speedup vs baseline: 1.0011x; 1.0011x over previous
; #define PG8_STAGE(bufoff, gbase, voff) do { _Pragma("unroll") for (int _i = 0; _i < 2; ++_i) \
;         __builtin_amdgcn_global_load_lds((const unsigned*)((const char*)(gbase) + (voff)[_i]), (PG8_LAS unsigned*)(lds + (bufoff) + ldsw + _i * 8192), 16, 0, 0); } while (0)
; #define PG8_LDA(dst, b, h) do { _Pragma("unroll") for (int m = 0; m < 4; ++m) _Pragma("unroll") for (int k = 0; k < 2; ++k) dst[m][k] = *(const PG8_LAS bf16x8*)(lds + PG8_SA(b, h) + aoff + m * 2048 + k * 1024); } while (0)
; #define PG8_LDB(dst, b, h) do { _Pragma("unroll") for (int n = 0; n < 2; ++n) _Pragma("unroll") for (int k = 0; k < 2; ++k) dst[n][k] = *(const PG8_LAS bf16x8*)(lds + PG8_SB(b, h) + boff + n * 2048 + k * 1024); } while (0)
; #define PG8_MMA(ai, bj, At, Bt) do { __builtin_amdgcn_s_setprio(1); _Pragma("unroll") for (int m = 0; m < 4; ++m) _Pragma("unroll") for (int n = 0; n < 2; ++n) _Pragma("unroll") for (int k = 0; k < 2; ++k) \
;         acc[ai][bj][m][n] = __builtin_amdgcn_mfma_f32_16x16x32_bf16(Bt[n][k], At[m][k], acc[ai][bj][m][n], 0, 0, 0); __builtin_amdgcn_s_setprio(0); } while (0)
; #define PG8_WAIT_V(n) asm volatile("s_waitcnt vmcnt(" #n ")" ::: "memory")
; #define PG8_WAIT_L(n) asm volatile("s_waitcnt lgkmcnt(" #n ")" ::: "memory")
; template <class Epi, class Sched, bool ALIGN_EPI = false, bool SP2 = false>
; __device__ __forceinline__ void gemm_phase(PG8_LAS unsigned char* lds, const Gemm g, const Sched& S, const Epi& E) {
;     ...
;             const bool last = (t == nt - 2);
;             const char* a1 = cA + (size_t)(t + 1) * kstep;
;             const char* a2 = last ? nA : cA + (size_t)(t + 2) * kstep; const char* b2 = last ? nB : cB + (size_t)(t + 2) * kstep;
;             const char* a3 = a2 + kstep; const char* b3 = b2 + kstep;
;             if (last && has_next) S.a_ready(nxt);
;             if constexpr (SP2) {
;             PG8_LDB(B0, 0, 0); PG8_LDB(B1, 0, 1); PG8_SCHED; PG8_LDA(At, 0, 0); PG8_STAGE(PG8_SA(1, 1), a1 + hstep, voffA);
;             PG8_WAIT_V(8); PG8_WAIT_L(0); PG8_BAR; PG8_MMA(0, 0, At, B0); PG8_MMA(0, 1, At, B1); PG8_BAR; PG8_SCHED;
;             PG8_LDA(At, 0, 1); PG8_STAGE(PG8_SB(0, 0), b2, voffB); PG8_STAGE(PG8_SB(0, 1), b2 + hstep, voffB); PG8_STAGE(PG8_SA(0, 0), a2, voffA);
;             PG8_WAIT_V(8); PG8_WAIT_L(0); PG8_BAR; PG8_MMA(1, 0, At, B0); PG8_MMA(1, 1, At, B1); PG8_BAR; PG8_SCHED;
.LBB0_134:
	ds_read_b128 v[136:139], v151
	ds_read_b128 v[168:171], v151 offset:1024
	ds_read_b128 v[176:179], v151 offset:2048
	ds_read_b128 v[180:183], v151 offset:3072
	ds_read_b128 v[184:187], v164
	ds_read_b128 v[188:191], v164 offset:1024
	ds_read_b128 v[192:195], v164 offset:2048
	ds_read_b128 v[196:199], v164 offset:3072
	s_add_u32 s36, s34, 0xfffc0080
	s_addc_u32 s37, s35, -1
	s_cmp_eq_u32 s89, 12
	s_cselect_b32 s39, s1, s37
	s_cselect_b32 s38, s7, s36
	s_cselect_b32 s37, s15, s88
	s_cselect_b32 s36, s27, s87
	v_lshl_add_u64 v[228:229], s[34:35], 0, v[128:129]
	s_add_i32 m0, s33, 0xc000
	ds_read_b128 v[200:203], v165
	ds_read_b128 v[204:207], v165 offset:1024
	ds_read_b128 v[208:211], v165 offset:2048
	ds_read_b128 v[212:215], v165 offset:3072
	ds_read_b128 v[216:219], v165 offset:4096
	ds_read_b128 v[220:223], v165 offset:5120
	ds_read_b128 v[224:227], v165 offset:6144
	ds_read_b128 v[240:243], v165 offset:7168
	global_load_lds_dwordx4 v[228:229], off
	v_lshl_add_u64 v[228:229], s[34:35], 0, v[130:131]
	s_add_i32 m0, s33, 0xe000
	s_nop 0
	global_load_lds_dwordx4 v[228:229], off
	s_waitcnt vmcnt(8)
	s_waitcnt lgkmcnt(0)
	s_setprio 1
	s_barrier
	v_mfma_f32_16x16x32_bf16 v[124:127], v[136:139], v[200:203], v[124:127]
	v_mfma_f32_16x16x32_bf16 v[116:119], v[176:179], v[200:203], v[116:119]
	v_mfma_f32_16x16x32_bf16 v[108:111], v[136:139], v[208:211], v[108:111]
	v_mfma_f32_16x16x32_bf16 v[100:103], v[176:179], v[208:211], v[100:103]
	v_mfma_f32_16x16x32_bf16 v[92:95], v[136:139], v[216:219], v[92:95]
	v_mfma_f32_16x16x32_bf16 v[84:87], v[176:179], v[216:219], v[84:87]
	v_mfma_f32_16x16x32_bf16 v[76:79], v[136:139], v[224:227], v[76:79]
	v_mfma_f32_16x16x32_bf16 v[68:71], v[176:179], v[224:227], v[68:71]
	v_mfma_f32_16x16x32_bf16 v[124:127], v[168:171], v[204:207], v[124:127]
	v_mfma_f32_16x16x32_bf16 v[116:119], v[180:183], v[204:207], v[116:119]
	v_mfma_f32_16x16x32_bf16 v[108:111], v[168:171], v[212:215], v[108:111]
	v_mfma_f32_16x16x32_bf16 v[100:103], v[180:183], v[212:215], v[100:103]
	v_mfma_f32_16x16x32_bf16 v[92:95], v[168:171], v[220:223], v[92:95]
	v_mfma_f32_16x16x32_bf16 v[84:87], v[180:183], v[220:223], v[84:87]
	v_mfma_f32_16x16x32_bf16 v[76:79], v[168:171], v[240:243], v[76:79]
	v_mfma_f32_16x16x32_bf16 v[68:71], v[180:183], v[240:243], v[68:71]
	s_setprio 0
	s_setprio 1
	v_mfma_f32_16x16x32_bf16 v[120:123], v[184:187], v[200:203], v[120:123]
	v_mfma_f32_16x16x32_bf16 v[112:115], v[192:195], v[200:203], v[112:115]
	v_mfma_f32_16x16x32_bf16 v[104:107], v[184:187], v[208:211], v[104:107]
	v_mfma_f32_16x16x32_bf16 v[96:99], v[192:195], v[208:211], v[96:99]
	v_mfma_f32_16x16x32_bf16 v[88:91], v[184:187], v[216:219], v[88:91]
	v_mfma_f32_16x16x32_bf16 v[80:83], v[192:195], v[216:219], v[80:83]
	v_mfma_f32_16x16x32_bf16 v[72:75], v[184:187], v[224:227], v[72:75]
	v_mfma_f32_16x16x32_bf16 v[64:67], v[192:195], v[224:227], v[64:67]
	v_mfma_f32_16x16x32_bf16 v[120:123], v[188:191], v[204:207], v[120:123]
	v_mfma_f32_16x16x32_bf16 v[112:115], v[196:199], v[204:207], v[112:115]
	v_mfma_f32_16x16x32_bf16 v[104:107], v[188:191], v[212:215], v[104:107]
	v_mfma_f32_16x16x32_bf16 v[96:99], v[196:199], v[212:215], v[96:99]
	v_mfma_f32_16x16x32_bf16 v[88:91], v[188:191], v[220:223], v[88:91]
	v_mfma_f32_16x16x32_bf16 v[80:83], v[196:199], v[220:223], v[80:83]
	v_mfma_f32_16x16x32_bf16 v[72:75], v[188:191], v[240:243], v[72:75]
	v_mfma_f32_16x16x32_bf16 v[64:67], v[196:199], v[240:243], v[64:67]
	s_barrier
	s_setprio 0
	s_add_i32 s90, s82, s3
	v_lshl_add_u64 v[228:229], s[36:37], 0, v[158:159]
	s_mov_b32 m0, s90
	ds_read_b128 v[200:203], v165 offset:16384
	ds_read_b128 v[204:207], v165 offset:17408
	ds_read_b128 v[208:211], v165 offset:18432
	ds_read_b128 v[212:215], v165 offset:19456
	ds_read_b128 v[216:219], v165 offset:20480
	ds_read_b128 v[220:223], v165 offset:21504
	ds_read_b128 v[224:227], v165 offset:22528
	ds_read_b128 v[240:243], v165 offset:23552
	global_load_lds_dwordx4 v[228:229], off
	s_add_i32 m0, s90, 0x2000
	s_add_u32 s90, s36, 0x40000
	v_lshl_add_u64 v[244:245], s[36:37], 0, v[162:163]
	s_addc_u32 s91, s37, 0
	s_add_i32 s93, s83, s3
	global_load_lds_dwordx4 v[244:245], off
	v_lshl_add_u64 v[248:249], s[90:91], 0, v[158:159]
	s_mov_b32 m0, s93
	v_lshl_add_u64 v[250:251], s[38:39], 0, v[160:161]
	global_load_lds_dwordx4 v[248:249], off
	v_lshl_add_u64 v[248:249], s[90:91], 0, v[162:163]
	s_add_i32 m0, s93, 0x2000
	s_nop 0
	global_load_lds_dwordx4 v[248:249], off
	v_lshl_add_u64 v[248:249], s[38:39], 0, v[156:157]
	s_mov_b32 m0, s33
	s_nop 0
	global_load_lds_dwordx4 v[248:249], off
	s_mov_b32 m0, s40
	s_nop 0
	global_load_lds_dwordx4 v[250:251], off
	s_waitcnt vmcnt(8)
	s_waitcnt lgkmcnt(0)
	s_setprio 1
	s_barrier
; #define PG8_STAGE(bufoff, gbase, voff) do { _Pragma("unroll") for (int _i = 0; _i < 2; ++_i) \
;         __builtin_amdgcn_global_load_lds((const unsigned*)((const char*)(gbase) + (voff)[_i]), (PG8_LAS unsigned*)(lds + (bufoff) + ldsw + _i * 8192), 16, 0, 0); } while (0)
; #define PG8_LDA(dst, b, h) do { _Pragma("unroll") for (int m = 0; m < 4; ++m) _Pragma("unroll") for (int k = 0; k < 2; ++k) dst[m][k] = *(const PG8_LAS bf16x8*)(lds + PG8_SA(b, h) + aoff + m * 2048 + k * 1024); } while (0)
; #define PG8_LDB(dst, b, h) do { _Pragma("unroll") for (int n = 0; n < 2; ++n) _Pragma("unroll") for (int k = 0; k < 2; ++k) dst[n][k] = *(const PG8_LAS bf16x8*)(lds + PG8_SB(b, h) + boff + n * 2048 + k * 1024); } while (0)
; #define PG8_MMA(ai, bj, At, Bt) do { __builtin_amdgcn_s_setprio(1); _Pragma("unroll") for (int m = 0; m < 4; ++m) _Pragma("unroll") for (int n = 0; n < 2; ++n) _Pragma("unroll") for (int k = 0; k < 2; ++k) \
;         acc[ai][bj][m][n] = __builtin_amdgcn_mfma_f32_16x16x32_bf16(Bt[n][k], At[m][k], acc[ai][bj][m][n], 0, 0, 0); __builtin_amdgcn_s_setprio(0); } while (0)
; #define PG8_WAIT_V(n) asm volatile("s_waitcnt vmcnt(" #n ")" ::: "memory")
; #define PG8_WAIT_L(n) asm volatile("s_waitcnt lgkmcnt(" #n ")" ::: "memory")
; #define PG8_BAR __builtin_amdgcn_s_barrier()
; #define PG8_SCHED __builtin_amdgcn_sched_barrier(0)
; template <class Epi, class Sched, bool ALIGN_EPI = false, bool SP2 = false>
; __device__ __forceinline__ void gemm_phase(PG8_LAS unsigned char* lds, const Gemm g, const Sched& S, const Epi& E) {
;     ...
;             PG8_WAIT_V(8); PG8_WAIT_L(0); PG8_BAR; PG8_MMA(1, 0, At, B0); PG8_MMA(1, 1, At, B1); PG8_BAR; PG8_SCHED;
;             PG8_LDB(B0, 1, 0); PG8_LDB(B1, 1, 1); PG8_SCHED; PG8_LDA(At, 1, 0); PG8_STAGE(PG8_SA(0, 1), a2 + hstep, voffA);
;             PG8_WAIT_V(8); PG8_WAIT_L(0); PG8_BAR; PG8_MMA(0, 0, At, B0); PG8_MMA(0, 1, At, B1); PG8_BAR; PG8_SCHED;
	v_mfma_f32_16x16x32_bf16 v[60:63], v[136:139], v[200:203], v[60:63]
	v_mfma_f32_16x16x32_bf16 v[52:55], v[176:179], v[200:203], v[52:55]
	v_mfma_f32_16x16x32_bf16 v[44:47], v[136:139], v[208:211], v[44:47]
	v_mfma_f32_16x16x32_bf16 v[36:39], v[176:179], v[208:211], v[36:39]
	v_mfma_f32_16x16x32_bf16 v[28:31], v[136:139], v[216:219], v[28:31]
	v_mfma_f32_16x16x32_bf16 v[20:23], v[176:179], v[216:219], v[20:23]
	v_mfma_f32_16x16x32_bf16 v[12:15], v[136:139], v[224:227], v[12:15]
	v_mfma_f32_16x16x32_bf16 v[4:7], v[176:179], v[224:227], v[4:7]
	v_mfma_f32_16x16x32_bf16 v[60:63], v[168:171], v[204:207], v[60:63]
	v_mfma_f32_16x16x32_bf16 v[52:55], v[180:183], v[204:207], v[52:55]
	v_mfma_f32_16x16x32_bf16 v[44:47], v[168:171], v[212:215], v[44:47]
	v_mfma_f32_16x16x32_bf16 v[36:39], v[180:183], v[212:215], v[36:39]
	v_mfma_f32_16x16x32_bf16 v[28:31], v[168:171], v[220:223], v[28:31]
	v_mfma_f32_16x16x32_bf16 v[20:23], v[180:183], v[220:223], v[20:23]
	v_mfma_f32_16x16x32_bf16 v[12:15], v[168:171], v[240:243], v[12:15]
	v_mfma_f32_16x16x32_bf16 v[4:7], v[180:183], v[240:243], v[4:7]
	s_setprio 0
	s_setprio 1
	v_mfma_f32_16x16x32_bf16 v[56:59], v[184:187], v[200:203], v[56:59]
	v_mfma_f32_16x16x32_bf16 v[48:51], v[192:195], v[200:203], v[48:51]
	v_mfma_f32_16x16x32_bf16 v[40:43], v[184:187], v[208:211], v[40:43]
	v_mfma_f32_16x16x32_bf16 v[32:35], v[192:195], v[208:211], v[32:35]
	v_mfma_f32_16x16x32_bf16 v[24:27], v[184:187], v[216:219], v[24:27]
	v_mfma_f32_16x16x32_bf16 v[16:19], v[192:195], v[216:219], v[16:19]
	v_mfma_f32_16x16x32_bf16 v[8:11], v[184:187], v[224:227], v[8:11]
	v_mfma_f32_16x16x32_bf16 v[0:3], v[192:195], v[224:227], v[0:3]
	v_mfma_f32_16x16x32_bf16 v[56:59], v[188:191], v[204:207], v[56:59]
	v_mfma_f32_16x16x32_bf16 v[48:51], v[196:199], v[204:207], v[48:51]
	v_mfma_f32_16x16x32_bf16 v[40:43], v[188:191], v[212:215], v[40:43]
	v_mfma_f32_16x16x32_bf16 v[32:35], v[196:199], v[212:215], v[32:35]
	v_mfma_f32_16x16x32_bf16 v[24:27], v[188:191], v[220:223], v[24:27]
	v_mfma_f32_16x16x32_bf16 v[16:19], v[196:199], v[220:223], v[16:19]
	v_mfma_f32_16x16x32_bf16 v[8:11], v[188:191], v[240:243], v[8:11]
	v_mfma_f32_16x16x32_bf16 v[0:3], v[196:199], v[240:243], v[0:3]
	s_barrier
	s_setprio 0
	s_add_i32 s90, 0, 0x18000
	v_add_u32_e32 v172, s90, v148
	s_add_i32 s91, 0, 0x1c000
	ds_read_b128 v[136:139], v172
	ds_read_b128 v[168:171], v172 offset:1024
	ds_read_b128 v[176:179], v172 offset:2048
	ds_read_b128 v[180:183], v172 offset:3072
	v_add_u32_e32 v172, s91, v148
	ds_read_b128 v[184:187], v172
	ds_read_b128 v[188:191], v172 offset:1024
	ds_read_b128 v[192:195], v172 offset:2048
	ds_read_b128 v[196:199], v172 offset:3072
	s_add_u32 s38, s38, 0x40000
	s_addc_u32 s39, s39, 0
	s_mov_b32 m0, s41
	v_lshl_add_u64 v[252:253], s[38:39], 0, v[156:157]
	ds_read_b128 v[200:203], v165 offset:32768
	ds_read_b128 v[204:207], v165 offset:33792
	ds_read_b128 v[208:211], v165 offset:34816
	ds_read_b128 v[212:215], v165 offset:35840
	ds_read_b128 v[216:219], v165 offset:36864
	ds_read_b128 v[220:223], v165 offset:37888
	ds_read_b128 v[224:227], v165 offset:38912
	ds_read_b128 v[240:243], v165 offset:39936
	global_load_lds_dwordx4 v[252:253], off
	v_lshl_add_u64 v[252:253], s[38:39], 0, v[160:161]
	s_mov_b32 m0, s42
	s_nop 0
	global_load_lds_dwordx4 v[252:253], off
	s_waitcnt vmcnt(8)
	s_waitcnt lgkmcnt(0)
	s_setprio 1
	s_barrier
	v_mfma_f32_16x16x32_bf16 v[124:127], v[136:139], v[200:203], v[124:127]
	v_mfma_f32_16x16x32_bf16 v[116:119], v[176:179], v[200:203], v[116:119]
	v_mfma_f32_16x16x32_bf16 v[108:111], v[136:139], v[208:211], v[108:111]
	v_mfma_f32_16x16x32_bf16 v[100:103], v[176:179], v[208:211], v[100:103]
	v_mfma_f32_16x16x32_bf16 v[92:95], v[136:139], v[216:219], v[92:95]
	v_mfma_f32_16x16x32_bf16 v[84:87], v[176:179], v[216:219], v[84:87]
	v_mfma_f32_16x16x32_bf16 v[76:79], v[136:139], v[224:227], v[76:79]
	v_mfma_f32_16x16x32_bf16 v[68:71], v[176:179], v[224:227], v[68:71]
	v_mfma_f32_16x16x32_bf16 v[124:127], v[168:171], v[204:207], v[124:127]
	v_mfma_f32_16x16x32_bf16 v[116:119], v[180:183], v[204:207], v[116:119]
	v_mfma_f32_16x16x32_bf16 v[108:111], v[168:171], v[212:215], v[108:111]
	v_mfma_f32_16x16x32_bf16 v[100:103], v[180:183], v[212:215], v[100:103]
	v_mfma_f32_16x16x32_bf16 v[92:95], v[168:171], v[220:223], v[92:95]
	v_mfma_f32_16x16x32_bf16 v[84:87], v[180:183], v[220:223], v[84:87]
	v_mfma_f32_16x16x32_bf16 v[76:79], v[168:171], v[240:243], v[76:79]
	v_mfma_f32_16x16x32_bf16 v[68:71], v[180:183], v[240:243], v[68:71]
	s_setprio 0
	s_setprio 1
	v_mfma_f32_16x16x32_bf16 v[120:123], v[184:187], v[200:203], v[120:123]
	v_mfma_f32_16x16x32_bf16 v[112:115], v[192:195], v[200:203], v[112:115]
	v_mfma_f32_16x16x32_bf16 v[104:107], v[184:187], v[208:211], v[104:107]
	v_mfma_f32_16x16x32_bf16 v[96:99], v[192:195], v[208:211], v[96:99]
	v_mfma_f32_16x16x32_bf16 v[88:91], v[184:187], v[216:219], v[88:91]
	v_mfma_f32_16x16x32_bf16 v[80:83], v[192:195], v[216:219], v[80:83]
	v_mfma_f32_16x16x32_bf16 v[72:75], v[184:187], v[224:227], v[72:75]
	v_mfma_f32_16x16x32_bf16 v[64:67], v[192:195], v[224:227], v[64:67]
	v_mfma_f32_16x16x32_bf16 v[120:123], v[188:191], v[204:207], v[120:123]
	v_mfma_f32_16x16x32_bf16 v[112:115], v[196:199], v[204:207], v[112:115]
	v_mfma_f32_16x16x32_bf16 v[104:107], v[188:191], v[212:215], v[104:107]
	v_mfma_f32_16x16x32_bf16 v[96:99], v[196:199], v[212:215], v[96:99]
	v_mfma_f32_16x16x32_bf16 v[88:91], v[188:191], v[220:223], v[88:91]
	v_mfma_f32_16x16x32_bf16 v[80:83], v[196:199], v[220:223], v[80:83]
	v_mfma_f32_16x16x32_bf16 v[72:75], v[188:191], v[240:243], v[72:75]
	v_mfma_f32_16x16x32_bf16 v[64:67], v[196:199], v[240:243], v[64:67]
	s_barrier
; #define PG8_STAGE(bufoff, gbase, voff) do { _Pragma("unroll") for (int _i = 0; _i < 2; ++_i) \
;         __builtin_amdgcn_global_load_lds((const unsigned*)((const char*)(gbase) + (voff)[_i]), (PG8_LAS unsigned*)(lds + (bufoff) + ldsw + _i * 8192), 16, 0, 0); } while (0)
; #define PG8_LDA(dst, b, h) do { _Pragma("unroll") for (int m = 0; m < 4; ++m) _Pragma("unroll") for (int k = 0; k < 2; ++k) dst[m][k] = *(const PG8_LAS bf16x8*)(lds + PG8_SA(b, h) + aoff + m * 2048 + k * 1024); } while (0)
; #define PG8_MMA(ai, bj, At, Bt) do { __builtin_amdgcn_s_setprio(1); _Pragma("unroll") for (int m = 0; m < 4; ++m) _Pragma("unroll") for (int n = 0; n < 2; ++n) _Pragma("unroll") for (int k = 0; k < 2; ++k) \
;         acc[ai][bj][m][n] = __builtin_amdgcn_mfma_f32_16x16x32_bf16(Bt[n][k], At[m][k], acc[ai][bj][m][n], 0, 0, 0); __builtin_amdgcn_s_setprio(0); } while (0)
; #define PG8_WAIT_V(n) asm volatile("s_waitcnt vmcnt(" #n ")" ::: "memory")
; #define PG8_WAIT_L(n) asm volatile("s_waitcnt lgkmcnt(" #n ")" ::: "memory")
; #define PG8_BAR __builtin_amdgcn_s_barrier()
; #define PG8_SCHED __builtin_amdgcn_sched_barrier(0)
; template <class Epi, class Sched, bool ALIGN_EPI = false, bool SP2 = false>
; __device__ __forceinline__ void gemm_phase(PG8_LAS unsigned char* lds, const Gemm g, const Sched& S, const Epi& E) {
;     ...
;             PG8_LDA(At, 1, 1); PG8_STAGE(PG8_SB(1, 0), b3, voffB); PG8_STAGE(PG8_SB(1, 1), b3 + hstep, voffB); PG8_STAGE(PG8_SA(1, 0), a3, voffA);
;             PG8_WAIT_V(8); PG8_WAIT_L(0); PG8_BAR; PG8_MMA(1, 0, At, B0); PG8_MMA(1, 1, At, B1); PG8_BAR; PG8_SCHED;
;     ...
;         if constexpr (ALIGN_EPI) { if (wr == 0) PG8_BAR; }
	s_setprio 0
	s_add_i32 s38, s90, s3
	v_lshl_add_u64 v[228:229], v[228:229], 0, s[10:11]
	s_mov_b32 m0, s38
	ds_read_b128 v[200:203], v165 offset:49152
	ds_read_b128 v[204:207], v165 offset:50176
	ds_read_b128 v[208:211], v165 offset:51200
	ds_read_b128 v[212:215], v165 offset:52224
	ds_read_b128 v[216:219], v165 offset:53248
	ds_read_b128 v[220:223], v165 offset:54272
	ds_read_b128 v[224:227], v165 offset:55296
	ds_read_b128 v[240:243], v165 offset:56320
	global_load_lds_dwordx4 v[228:229], off
	s_add_i32 m0, s38, 0x2000
	s_add_u32 s36, s36, 0x40080
	v_lshl_add_u64 v[228:229], v[244:245], 0, s[10:11]
	s_addc_u32 s37, s37, 0
	s_add_i32 s38, s91, s3
	global_load_lds_dwordx4 v[228:229], off
	v_lshl_add_u64 v[228:229], s[36:37], 0, v[158:159]
	s_mov_b32 m0, s38
	s_nop 0
	global_load_lds_dwordx4 v[228:229], off
	v_lshl_add_u64 v[228:229], s[36:37], 0, v[162:163]
	s_add_i32 m0, s38, 0x2000
	s_nop 0
	global_load_lds_dwordx4 v[228:229], off
	v_lshl_add_u64 v[228:229], v[248:249], 0, s[10:11]
	s_mov_b32 m0, s44
	s_nop 0
	global_load_lds_dwordx4 v[228:229], off
	v_lshl_add_u64 v[228:229], v[250:251], 0, s[10:11]
	s_mov_b32 m0, s45
	s_nop 0
	global_load_lds_dwordx4 v[228:229], off
	s_waitcnt vmcnt(8)
	s_waitcnt lgkmcnt(0)
	s_setprio 1
	s_barrier
	v_mfma_f32_16x16x32_bf16 v[60:63], v[136:139], v[200:203], v[60:63]
	v_mfma_f32_16x16x32_bf16 v[52:55], v[176:179], v[200:203], v[52:55]
	v_mfma_f32_16x16x32_bf16 v[44:47], v[136:139], v[208:211], v[44:47]
	v_mfma_f32_16x16x32_bf16 v[36:39], v[176:179], v[208:211], v[36:39]
	v_mfma_f32_16x16x32_bf16 v[28:31], v[136:139], v[216:219], v[28:31]
	v_mfma_f32_16x16x32_bf16 v[20:23], v[176:179], v[216:219], v[20:23]
	v_mfma_f32_16x16x32_bf16 v[12:15], v[136:139], v[224:227], v[12:15]
	v_mfma_f32_16x16x32_bf16 v[4:7], v[176:179], v[224:227], v[4:7]
	v_mfma_f32_16x16x32_bf16 v[60:63], v[168:171], v[204:207], v[60:63]
	v_mfma_f32_16x16x32_bf16 v[52:55], v[180:183], v[204:207], v[52:55]
	v_mfma_f32_16x16x32_bf16 v[44:47], v[168:171], v[212:215], v[44:47]
	v_mfma_f32_16x16x32_bf16 v[36:39], v[180:183], v[212:215], v[36:39]
	v_mfma_f32_16x16x32_bf16 v[28:31], v[168:171], v[220:223], v[28:31]
	v_mfma_f32_16x16x32_bf16 v[20:23], v[180:183], v[220:223], v[20:23]
	v_mfma_f32_16x16x32_bf16 v[12:15], v[168:171], v[240:243], v[12:15]
	v_mfma_f32_16x16x32_bf16 v[4:7], v[180:183], v[240:243], v[4:7]
	s_setprio 0
	s_setprio 1
	v_mfma_f32_16x16x32_bf16 v[56:59], v[184:187], v[200:203], v[56:59]
	v_mfma_f32_16x16x32_bf16 v[48:51], v[192:195], v[200:203], v[48:51]
	v_mfma_f32_16x16x32_bf16 v[40:43], v[184:187], v[208:211], v[40:43]
	v_mfma_f32_16x16x32_bf16 v[32:35], v[192:195], v[208:211], v[32:35]
	v_mfma_f32_16x16x32_bf16 v[24:27], v[184:187], v[216:219], v[24:27]
	v_mfma_f32_16x16x32_bf16 v[16:19], v[192:195], v[216:219], v[16:19]
	v_mfma_f32_16x16x32_bf16 v[8:11], v[184:187], v[224:227], v[8:11]
	v_mfma_f32_16x16x32_bf16 v[0:3], v[192:195], v[224:227], v[0:3]
	v_mfma_f32_16x16x32_bf16 v[56:59], v[188:191], v[204:207], v[56:59]
	v_mfma_f32_16x16x32_bf16 v[48:51], v[196:199], v[204:207], v[48:51]
	v_mfma_f32_16x16x32_bf16 v[40:43], v[188:191], v[212:215], v[40:43]
	v_mfma_f32_16x16x32_bf16 v[32:35], v[196:199], v[212:215], v[32:35]
	v_mfma_f32_16x16x32_bf16 v[24:27], v[188:191], v[220:223], v[24:27]
	v_mfma_f32_16x16x32_bf16 v[16:19], v[196:199], v[220:223], v[16:19]
	v_mfma_f32_16x16x32_bf16 v[8:11], v[188:191], v[240:243], v[8:11]
	v_mfma_f32_16x16x32_bf16 v[0:3], v[196:199], v[240:243], v[0:3]
	s_barrier
	s_setprio 0
	s_add_i32 s89, s89, 2
	s_add_u32 s34, s34, 0x100
	s_addc_u32 s35, s35, 0
	s_add_u32 s87, s87, 0x100
	s_addc_u32 s88, s88, 0
	s_cmp_gt_u32 s89, 13
	s_cbranch_scc0 .LBB0_134
	s_and_b64 vcc, exec, s[12:13]
	s_cbranch_vccz .LBB0_137
	s_barrier

; #define PG8_STAGE(bufoff, gbase, voff) do { _Pragma("unroll") for (int _i = 0; _i < 2; ++_i) \
;         __builtin_amdgcn_global_load_lds((const unsigned*)((const char*)(gbase) + (voff)[_i]), (PG8_LAS unsigned*)(lds + (bufoff) + ldsw + _i * 8192), 16, 0, 0); } while (0)
; #define PG8_LDA(dst, b, h) do { _Pragma("unroll") for (int m = 0; m < 4; ++m) _Pragma("unroll") for (int k = 0; k < 2; ++k) dst[m][k] = *(const PG8_LAS bf16x8*)(lds + PG8_SA(b, h) + aoff + m * 2048 + k * 1024); } while (0)
; #define PG8_LDB(dst, b, h) do { _Pragma("unroll") for (int n = 0; n < 2; ++n) _Pragma("unroll") for (int k = 0; k < 2; ++k) dst[n][k] = *(const PG8_LAS bf16x8*)(lds + PG8_SB(b, h) + boff + n * 2048 + k * 1024); } while (0)
; #define PG8_MMA(ai, bj, At, Bt) do { __builtin_amdgcn_s_setprio(1); _Pragma("unroll") for (int m = 0; m < 4; ++m) _Pragma("unroll") for (int n = 0; n < 2; ++n) _Pragma("unroll") for (int k = 0; k < 2; ++k) \
;         acc[ai][bj][m][n] = __builtin_amdgcn_mfma_f32_16x16x32_bf16(Bt[n][k], At[m][k], acc[ai][bj][m][n], 0, 0, 0); __builtin_amdgcn_s_setprio(0); } while (0)
; #define PG8_WAIT_V(n) asm volatile("s_waitcnt vmcnt(" #n ")" ::: "memory")
; #define PG8_WAIT_L(n) asm volatile("s_waitcnt lgkmcnt(" #n ")" ::: "memory")
; template <class Epi, class Sched, bool ALIGN_EPI = false, bool SP2 = false>
; __device__ __forceinline__ void gemm_phase(PG8_LAS unsigned char* lds, const Gemm g, const Sched& S, const Epi& E) {
;     ...
;             const bool last = (t == nt - 2);
;             const char* a1 = cA + (size_t)(t + 1) * kstep;
;             const char* a2 = last ? nA : cA + (size_t)(t + 2) * kstep; const char* b2 = last ? nB : cB + (size_t)(t + 2) * kstep;
;             const char* a3 = a2 + kstep; const char* b3 = b2 + kstep;
;             if (last && has_next) S.a_ready(nxt);
;             if constexpr (SP2) {
;             PG8_LDB(B0, 0, 0); PG8_LDB(B1, 0, 1); PG8_SCHED; PG8_LDA(At, 0, 0); PG8_STAGE(PG8_SA(1, 1), a1 + hstep, voffA);
;             PG8_WAIT_V(8); PG8_WAIT_L(0); PG8_BAR; PG8_MMA(0, 0, At, B0); PG8_MMA(0, 1, At, B1); PG8_BAR; PG8_SCHED;
;             PG8_LDA(At, 0, 1); PG8_STAGE(PG8_SB(0, 0), b2, voffB); PG8_STAGE(PG8_SB(0, 1), b2 + hstep, voffB); PG8_STAGE(PG8_SA(0, 0), a2, voffA);
;             PG8_WAIT_V(8); PG8_WAIT_L(0); PG8_BAR; PG8_MMA(1, 0, At, B0); PG8_MMA(1, 1, At, B1); PG8_BAR; PG8_SCHED;
.LBB0_372:
	ds_read_b128 v[128:131], v161
	ds_read_b128 v[132:135], v161 offset:1024
	ds_read_b128 v[136:139], v161 offset:2048
	ds_read_b128 v[140:143], v161 offset:3072
	ds_read_b128 v[144:147], v163
	ds_read_b128 v[148:151], v163 offset:1024
	ds_read_b128 v[184:187], v163 offset:2048
	ds_read_b128 v[188:191], v163 offset:3072
	s_add_u32 s24, s20, 0xfff50080
	s_addc_u32 s25, s21, -1
	s_cmp_eq_u32 s54, 40
	s_cselect_b32 s27, s1, s25
	s_cselect_b32 s26, s0, s24
	s_cselect_b32 s25, s19, s47
	s_cselect_b32 s24, s18, s46
	v_lshl_add_u64 v[200:201], s[20:21], 0, v[176:177]
	s_add_i32 m0, s29, 0xc000
	ds_read_b128 v[192:195], v202
	ds_read_b128 v[196:199], v202 offset:1024
	ds_read_b128 v[204:207], v202 offset:2048
	ds_read_b128 v[208:211], v202 offset:3072
	ds_read_b128 v[212:215], v202 offset:4096
	ds_read_b128 v[216:219], v202 offset:5120
	ds_read_b128 v[220:223], v202 offset:6144
	ds_read_b128 v[224:227], v202 offset:7168
	global_load_lds_dwordx4 v[200:201], off
	v_lshl_add_u64 v[200:201], s[20:21], 0, v[178:179]
	s_add_i32 m0, s29, 0xe000
	s_nop 0
	global_load_lds_dwordx4 v[200:201], off
	s_waitcnt vmcnt(8)
	s_waitcnt lgkmcnt(0)
	s_setprio 1
	s_barrier
	v_mfma_f32_16x16x32_bf16 v[124:127], v[128:131], v[192:195], v[124:127]
	v_mfma_f32_16x16x32_bf16 v[120:123], v[136:139], v[192:195], v[120:123]
	v_mfma_f32_16x16x32_bf16 v[108:111], v[128:131], v[204:207], v[108:111]
	v_mfma_f32_16x16x32_bf16 v[104:107], v[136:139], v[204:207], v[104:107]
	v_mfma_f32_16x16x32_bf16 v[92:95], v[128:131], v[212:215], v[92:95]
	v_mfma_f32_16x16x32_bf16 v[88:91], v[136:139], v[212:215], v[88:91]
	v_mfma_f32_16x16x32_bf16 v[76:79], v[128:131], v[220:223], v[76:79]
	v_mfma_f32_16x16x32_bf16 v[72:75], v[136:139], v[220:223], v[72:75]
	v_mfma_f32_16x16x32_bf16 v[124:127], v[132:135], v[196:199], v[124:127]
	v_mfma_f32_16x16x32_bf16 v[120:123], v[140:143], v[196:199], v[120:123]
	v_mfma_f32_16x16x32_bf16 v[108:111], v[132:135], v[208:211], v[108:111]
	v_mfma_f32_16x16x32_bf16 v[104:107], v[140:143], v[208:211], v[104:107]
	v_mfma_f32_16x16x32_bf16 v[92:95], v[132:135], v[216:219], v[92:95]
	v_mfma_f32_16x16x32_bf16 v[88:91], v[140:143], v[216:219], v[88:91]
	v_mfma_f32_16x16x32_bf16 v[76:79], v[132:135], v[224:227], v[76:79]
	v_mfma_f32_16x16x32_bf16 v[72:75], v[140:143], v[224:227], v[72:75]
	s_setprio 0
	s_setprio 1
	v_mfma_f32_16x16x32_bf16 v[116:119], v[144:147], v[192:195], v[116:119]
	v_mfma_f32_16x16x32_bf16 v[112:115], v[184:187], v[192:195], v[112:115]
	v_mfma_f32_16x16x32_bf16 v[100:103], v[144:147], v[204:207], v[100:103]
	v_mfma_f32_16x16x32_bf16 v[96:99], v[184:187], v[204:207], v[96:99]
	v_mfma_f32_16x16x32_bf16 v[84:87], v[144:147], v[212:215], v[84:87]
	v_mfma_f32_16x16x32_bf16 v[80:83], v[184:187], v[212:215], v[80:83]
	v_mfma_f32_16x16x32_bf16 v[68:71], v[144:147], v[220:223], v[68:71]
	v_mfma_f32_16x16x32_bf16 v[64:67], v[184:187], v[220:223], v[64:67]
	v_mfma_f32_16x16x32_bf16 v[116:119], v[148:151], v[196:199], v[116:119]
	v_mfma_f32_16x16x32_bf16 v[112:115], v[188:191], v[196:199], v[112:115]
	v_mfma_f32_16x16x32_bf16 v[100:103], v[148:151], v[208:211], v[100:103]
	v_mfma_f32_16x16x32_bf16 v[96:99], v[188:191], v[208:211], v[96:99]
	v_mfma_f32_16x16x32_bf16 v[84:87], v[148:151], v[216:219], v[84:87]
	v_mfma_f32_16x16x32_bf16 v[80:83], v[188:191], v[216:219], v[80:83]
	v_mfma_f32_16x16x32_bf16 v[68:71], v[148:151], v[224:227], v[68:71]
	v_mfma_f32_16x16x32_bf16 v[64:67], v[188:191], v[224:227], v[64:67]
	s_barrier
	s_setprio 0
	s_add_i32 s55, s40, s28
	v_lshl_add_u64 v[200:201], s[24:25], 0, v[166:167]
	s_mov_b32 m0, s55
	ds_read_b128 v[192:195], v202 offset:16384
	ds_read_b128 v[196:199], v202 offset:17408
	ds_read_b128 v[204:207], v202 offset:18432
	ds_read_b128 v[208:211], v202 offset:19456
	ds_read_b128 v[212:215], v202 offset:20480
	ds_read_b128 v[216:219], v202 offset:21504
	ds_read_b128 v[220:223], v202 offset:22528
	ds_read_b128 v[224:227], v202 offset:23552
	global_load_lds_dwordx4 v[200:201], off
	s_add_i32 m0, s55, 0x2000
	s_add_u32 s56, s24, 0xb0000
	v_lshl_add_u64 v[228:229], s[24:25], 0, v[170:171]
	s_addc_u32 s57, s25, 0
	s_add_i32 s55, s41, s28
	global_load_lds_dwordx4 v[228:229], off
	v_lshl_add_u64 v[248:249], s[56:57], 0, v[166:167]
	s_mov_b32 m0, s55
	v_lshl_add_u64 v[250:251], s[26:27], 0, v[168:169]
	global_load_lds_dwordx4 v[248:249], off
	v_lshl_add_u64 v[248:249], s[56:57], 0, v[170:171]
	s_add_i32 m0, s55, 0x2000
	s_nop 0
	global_load_lds_dwordx4 v[248:249], off
	v_lshl_add_u64 v[248:249], s[26:27], 0, v[164:165]
	s_mov_b32 m0, s29
	s_nop 0
	global_load_lds_dwordx4 v[248:249], off
	s_mov_b32 m0, s30
	s_nop 0
	global_load_lds_dwordx4 v[250:251], off
	s_waitcnt vmcnt(8)
	s_waitcnt lgkmcnt(0)
	s_setprio 1
	s_barrier
; #define PG8_STAGE(bufoff, gbase, voff) do { _Pragma("unroll") for (int _i = 0; _i < 2; ++_i) \
;         __builtin_amdgcn_global_load_lds((const unsigned*)((const char*)(gbase) + (voff)[_i]), (PG8_LAS unsigned*)(lds + (bufoff) + ldsw + _i * 8192), 16, 0, 0); } while (0)
; #define PG8_LDA(dst, b, h) do { _Pragma("unroll") for (int m = 0; m < 4; ++m) _Pragma("unroll") for (int k = 0; k < 2; ++k) dst[m][k] = *(const PG8_LAS bf16x8*)(lds + PG8_SA(b, h) + aoff + m * 2048 + k * 1024); } while (0)
; #define PG8_LDB(dst, b, h) do { _Pragma("unroll") for (int n = 0; n < 2; ++n) _Pragma("unroll") for (int k = 0; k < 2; ++k) dst[n][k] = *(const PG8_LAS bf16x8*)(lds + PG8_SB(b, h) + boff + n * 2048 + k * 1024); } while (0)
; #define PG8_MMA(ai, bj, At, Bt) do { __builtin_amdgcn_s_setprio(1); _Pragma("unroll") for (int m = 0; m < 4; ++m) _Pragma("unroll") for (int n = 0; n < 2; ++n) _Pragma("unroll") for (int k = 0; k < 2; ++k) \
;         acc[ai][bj][m][n] = __builtin_amdgcn_mfma_f32_16x16x32_bf16(Bt[n][k], At[m][k], acc[ai][bj][m][n], 0, 0, 0); __builtin_amdgcn_s_setprio(0); } while (0)
; #define PG8_WAIT_V(n) asm volatile("s_waitcnt vmcnt(" #n ")" ::: "memory")
; #define PG8_WAIT_L(n) asm volatile("s_waitcnt lgkmcnt(" #n ")" ::: "memory")
; #define PG8_BAR __builtin_amdgcn_s_barrier()
; #define PG8_SCHED __builtin_amdgcn_sched_barrier(0)
; template <class Epi, class Sched, bool ALIGN_EPI = false, bool SP2 = false>
; __device__ __forceinline__ void gemm_phase(PG8_LAS unsigned char* lds, const Gemm g, const Sched& S, const Epi& E) {
;     ...
;             PG8_WAIT_V(8); PG8_WAIT_L(0); PG8_BAR; PG8_MMA(1, 0, At, B0); PG8_MMA(1, 1, At, B1); PG8_BAR; PG8_SCHED;
;             PG8_LDB(B0, 1, 0); PG8_LDB(B1, 1, 1); PG8_SCHED; PG8_LDA(At, 1, 0); PG8_STAGE(PG8_SA(0, 1), a2 + hstep, voffA);
;             PG8_WAIT_V(8); PG8_WAIT_L(0); PG8_BAR; PG8_MMA(0, 0, At, B0); PG8_MMA(0, 1, At, B1); PG8_BAR; PG8_SCHED;
	v_mfma_f32_16x16x32_bf16 v[60:63], v[128:131], v[192:195], v[60:63]
	v_mfma_f32_16x16x32_bf16 v[56:59], v[136:139], v[192:195], v[56:59]
	v_mfma_f32_16x16x32_bf16 v[44:47], v[128:131], v[204:207], v[44:47]
	v_mfma_f32_16x16x32_bf16 v[40:43], v[136:139], v[204:207], v[40:43]
	v_mfma_f32_16x16x32_bf16 v[28:31], v[128:131], v[212:215], v[28:31]
	v_mfma_f32_16x16x32_bf16 v[24:27], v[136:139], v[212:215], v[24:27]
	v_mfma_f32_16x16x32_bf16 v[12:15], v[128:131], v[220:223], v[12:15]
	v_mfma_f32_16x16x32_bf16 v[8:11], v[136:139], v[220:223], v[8:11]
	v_mfma_f32_16x16x32_bf16 v[60:63], v[132:135], v[196:199], v[60:63]
	v_mfma_f32_16x16x32_bf16 v[56:59], v[140:143], v[196:199], v[56:59]
	v_mfma_f32_16x16x32_bf16 v[44:47], v[132:135], v[208:211], v[44:47]
	v_mfma_f32_16x16x32_bf16 v[40:43], v[140:143], v[208:211], v[40:43]
	v_mfma_f32_16x16x32_bf16 v[28:31], v[132:135], v[216:219], v[28:31]
	v_mfma_f32_16x16x32_bf16 v[24:27], v[140:143], v[216:219], v[24:27]
	v_mfma_f32_16x16x32_bf16 v[12:15], v[132:135], v[224:227], v[12:15]
	v_mfma_f32_16x16x32_bf16 v[8:11], v[140:143], v[224:227], v[8:11]
	s_setprio 0
	s_setprio 1
	v_mfma_f32_16x16x32_bf16 v[52:55], v[144:147], v[192:195], v[52:55]
	v_mfma_f32_16x16x32_bf16 v[48:51], v[184:187], v[192:195], v[48:51]
	v_mfma_f32_16x16x32_bf16 v[36:39], v[144:147], v[204:207], v[36:39]
	v_mfma_f32_16x16x32_bf16 v[32:35], v[184:187], v[204:207], v[32:35]
	v_mfma_f32_16x16x32_bf16 v[20:23], v[144:147], v[212:215], v[20:23]
	v_mfma_f32_16x16x32_bf16 v[16:19], v[184:187], v[212:215], v[16:19]
	v_mfma_f32_16x16x32_bf16 v[4:7], v[144:147], v[220:223], v[4:7]
	v_mfma_f32_16x16x32_bf16 v[0:3], v[184:187], v[220:223], v[0:3]
	v_mfma_f32_16x16x32_bf16 v[52:55], v[148:151], v[196:199], v[52:55]
	v_mfma_f32_16x16x32_bf16 v[48:51], v[188:191], v[196:199], v[48:51]
	v_mfma_f32_16x16x32_bf16 v[36:39], v[148:151], v[208:211], v[36:39]
	v_mfma_f32_16x16x32_bf16 v[32:35], v[188:191], v[208:211], v[32:35]
	v_mfma_f32_16x16x32_bf16 v[20:23], v[148:151], v[216:219], v[20:23]
	v_mfma_f32_16x16x32_bf16 v[16:19], v[188:191], v[216:219], v[16:19]
	v_mfma_f32_16x16x32_bf16 v[4:7], v[148:151], v[224:227], v[4:7]
	v_mfma_f32_16x16x32_bf16 v[0:3], v[188:191], v[224:227], v[0:3]
	s_barrier
	s_setprio 0
	s_add_i32 s55, 0, 0x18000
	s_add_i32 s56, 0, 0x1c000
	v_add_u32_e32 v140, s55, v159
	v_add_u32_e32 v188, s56, v159
	ds_read_b128 v[128:131], v140
	ds_read_b128 v[132:135], v140 offset:1024
	ds_read_b128 v[136:139], v140 offset:2048
	ds_read_b128 v[140:143], v140 offset:3072
	ds_read_b128 v[144:147], v188
	ds_read_b128 v[148:151], v188 offset:1024
	ds_read_b128 v[184:187], v188 offset:2048
	ds_read_b128 v[188:191], v188 offset:3072
	s_add_u32 s26, s26, 0xb0000
	s_addc_u32 s27, s27, 0
	s_mov_b32 m0, s31
	v_lshl_add_u64 v[252:253], s[26:27], 0, v[164:165]
	ds_read_b128 v[192:195], v202 offset:32768
	ds_read_b128 v[196:199], v202 offset:33792
	ds_read_b128 v[204:207], v202 offset:34816
	ds_read_b128 v[208:211], v202 offset:35840
	ds_read_b128 v[212:215], v202 offset:36864
	ds_read_b128 v[216:219], v202 offset:37888
	ds_read_b128 v[220:223], v202 offset:38912
	ds_read_b128 v[224:227], v202 offset:39936
	global_load_lds_dwordx4 v[252:253], off
	v_lshl_add_u64 v[252:253], s[26:27], 0, v[168:169]
	s_mov_b32 m0, s33
	s_nop 0
	global_load_lds_dwordx4 v[252:253], off
	s_waitcnt vmcnt(8)
	s_waitcnt lgkmcnt(0)
	s_setprio 1
	s_barrier
	v_mfma_f32_16x16x32_bf16 v[124:127], v[128:131], v[192:195], v[124:127]
	v_mfma_f32_16x16x32_bf16 v[120:123], v[136:139], v[192:195], v[120:123]
	v_mfma_f32_16x16x32_bf16 v[108:111], v[128:131], v[204:207], v[108:111]
	v_mfma_f32_16x16x32_bf16 v[104:107], v[136:139], v[204:207], v[104:107]
	v_mfma_f32_16x16x32_bf16 v[92:95], v[128:131], v[212:215], v[92:95]
	v_mfma_f32_16x16x32_bf16 v[88:91], v[136:139], v[212:215], v[88:91]
	v_mfma_f32_16x16x32_bf16 v[76:79], v[128:131], v[220:223], v[76:79]
	v_mfma_f32_16x16x32_bf16 v[72:75], v[136:139], v[220:223], v[72:75]
	v_mfma_f32_16x16x32_bf16 v[124:127], v[132:135], v[196:199], v[124:127]
	v_mfma_f32_16x16x32_bf16 v[120:123], v[140:143], v[196:199], v[120:123]
	v_mfma_f32_16x16x32_bf16 v[108:111], v[132:135], v[208:211], v[108:111]
	v_mfma_f32_16x16x32_bf16 v[104:107], v[140:143], v[208:211], v[104:107]
	v_mfma_f32_16x16x32_bf16 v[92:95], v[132:135], v[216:219], v[92:95]
	v_mfma_f32_16x16x32_bf16 v[88:91], v[140:143], v[216:219], v[88:91]
	v_mfma_f32_16x16x32_bf16 v[76:79], v[132:135], v[224:227], v[76:79]
	v_mfma_f32_16x16x32_bf16 v[72:75], v[140:143], v[224:227], v[72:75]
	s_setprio 0
	s_setprio 1
	v_mfma_f32_16x16x32_bf16 v[116:119], v[144:147], v[192:195], v[116:119]
	v_mfma_f32_16x16x32_bf16 v[112:115], v[184:187], v[192:195], v[112:115]
	v_mfma_f32_16x16x32_bf16 v[100:103], v[144:147], v[204:207], v[100:103]
	v_mfma_f32_16x16x32_bf16 v[96:99], v[184:187], v[204:207], v[96:99]
	v_mfma_f32_16x16x32_bf16 v[84:87], v[144:147], v[212:215], v[84:87]
	v_mfma_f32_16x16x32_bf16 v[80:83], v[184:187], v[212:215], v[80:83]
	v_mfma_f32_16x16x32_bf16 v[68:71], v[144:147], v[220:223], v[68:71]
	v_mfma_f32_16x16x32_bf16 v[64:67], v[184:187], v[220:223], v[64:67]
	v_mfma_f32_16x16x32_bf16 v[116:119], v[148:151], v[196:199], v[116:119]
	v_mfma_f32_16x16x32_bf16 v[112:115], v[188:191], v[196:199], v[112:115]
	v_mfma_f32_16x16x32_bf16 v[100:103], v[148:151], v[208:211], v[100:103]
	v_mfma_f32_16x16x32_bf16 v[96:99], v[188:191], v[208:211], v[96:99]
	v_mfma_f32_16x16x32_bf16 v[84:87], v[148:151], v[216:219], v[84:87]
	v_mfma_f32_16x16x32_bf16 v[80:83], v[188:191], v[216:219], v[80:83]
	v_mfma_f32_16x16x32_bf16 v[68:71], v[148:151], v[224:227], v[68:71]
	v_mfma_f32_16x16x32_bf16 v[64:67], v[188:191], v[224:227], v[64:67]
	s_barrier
; #define PG8_STAGE(bufoff, gbase, voff) do { _Pragma("unroll") for (int _i = 0; _i < 2; ++_i) \
;         __builtin_amdgcn_global_load_lds((const unsigned*)((const char*)(gbase) + (voff)[_i]), (PG8_LAS unsigned*)(lds + (bufoff) + ldsw + _i * 8192), 16, 0, 0); } while (0)
; #define PG8_LDA(dst, b, h) do { _Pragma("unroll") for (int m = 0; m < 4; ++m) _Pragma("unroll") for (int k = 0; k < 2; ++k) dst[m][k] = *(const PG8_LAS bf16x8*)(lds + PG8_SA(b, h) + aoff + m * 2048 + k * 1024); } while (0)
; #define PG8_MMA(ai, bj, At, Bt) do { __builtin_amdgcn_s_setprio(1); _Pragma("unroll") for (int m = 0; m < 4; ++m) _Pragma("unroll") for (int n = 0; n < 2; ++n) _Pragma("unroll") for (int k = 0; k < 2; ++k) \
;         acc[ai][bj][m][n] = __builtin_amdgcn_mfma_f32_16x16x32_bf16(Bt[n][k], At[m][k], acc[ai][bj][m][n], 0, 0, 0); __builtin_amdgcn_s_setprio(0); } while (0)
; #define PG8_WAIT_V(n) asm volatile("s_waitcnt vmcnt(" #n ")" ::: "memory")
; #define PG8_WAIT_L(n) asm volatile("s_waitcnt lgkmcnt(" #n ")" ::: "memory")
; #define PG8_BAR __builtin_amdgcn_s_barrier()
; #define PG8_SCHED __builtin_amdgcn_sched_barrier(0)
; template <class Epi, class Sched, bool ALIGN_EPI = false, bool SP2 = false>
; __device__ __forceinline__ void gemm_phase(PG8_LAS unsigned char* lds, const Gemm g, const Sched& S, const Epi& E) {
;     ...
;             PG8_LDA(At, 1, 1); PG8_STAGE(PG8_SB(1, 0), b3, voffB); PG8_STAGE(PG8_SB(1, 1), b3 + hstep, voffB); PG8_STAGE(PG8_SA(1, 0), a3, voffA);
;             PG8_WAIT_V(8); PG8_WAIT_L(0); PG8_BAR; PG8_MMA(1, 0, At, B0); PG8_MMA(1, 1, At, B1); PG8_BAR; PG8_SCHED;
;     ...
;         if constexpr (ALIGN_EPI) { if (wr == 0) PG8_BAR; }
	s_setprio 0
	s_add_i32 s26, s55, s28
	v_lshl_add_u64 v[200:201], v[200:201], 0, s[12:13]
	s_mov_b32 m0, s26
	ds_read_b128 v[192:195], v202 offset:49152
	ds_read_b128 v[196:199], v202 offset:50176
	ds_read_b128 v[204:207], v202 offset:51200
	ds_read_b128 v[208:211], v202 offset:52224
	ds_read_b128 v[212:215], v202 offset:53248
	ds_read_b128 v[216:219], v202 offset:54272
	ds_read_b128 v[220:223], v202 offset:55296
	ds_read_b128 v[224:227], v202 offset:56320
	global_load_lds_dwordx4 v[200:201], off
	s_add_i32 m0, s26, 0x2000
	s_add_u32 s24, s24, 0xb0080
	v_lshl_add_u64 v[200:201], v[228:229], 0, s[12:13]
	s_addc_u32 s25, s25, 0
	s_add_i32 s26, s56, s28
	global_load_lds_dwordx4 v[200:201], off
	v_lshl_add_u64 v[200:201], s[24:25], 0, v[166:167]
	s_mov_b32 m0, s26
	s_nop 0
	global_load_lds_dwordx4 v[200:201], off
	v_lshl_add_u64 v[200:201], s[24:25], 0, v[170:171]
	s_add_i32 m0, s26, 0x2000
	s_nop 0
	global_load_lds_dwordx4 v[200:201], off
	v_lshl_add_u64 v[200:201], v[248:249], 0, s[12:13]
	s_mov_b32 m0, s35
	s_nop 0
	global_load_lds_dwordx4 v[200:201], off
	v_lshl_add_u64 v[200:201], v[250:251], 0, s[12:13]
	s_mov_b32 m0, s36
	s_nop 0
	global_load_lds_dwordx4 v[200:201], off
	s_waitcnt vmcnt(8)
	s_waitcnt lgkmcnt(0)
	s_setprio 1
	s_barrier
	v_mfma_f32_16x16x32_bf16 v[60:63], v[128:131], v[192:195], v[60:63]
	v_mfma_f32_16x16x32_bf16 v[56:59], v[136:139], v[192:195], v[56:59]
	v_mfma_f32_16x16x32_bf16 v[44:47], v[128:131], v[204:207], v[44:47]
	v_mfma_f32_16x16x32_bf16 v[40:43], v[136:139], v[204:207], v[40:43]
	v_mfma_f32_16x16x32_bf16 v[28:31], v[128:131], v[212:215], v[28:31]
	v_mfma_f32_16x16x32_bf16 v[24:27], v[136:139], v[212:215], v[24:27]
	v_mfma_f32_16x16x32_bf16 v[12:15], v[128:131], v[220:223], v[12:15]
	v_mfma_f32_16x16x32_bf16 v[8:11], v[136:139], v[220:223], v[8:11]
	v_mfma_f32_16x16x32_bf16 v[60:63], v[132:135], v[196:199], v[60:63]
	v_mfma_f32_16x16x32_bf16 v[56:59], v[140:143], v[196:199], v[56:59]
	v_mfma_f32_16x16x32_bf16 v[44:47], v[132:135], v[208:211], v[44:47]
	v_mfma_f32_16x16x32_bf16 v[40:43], v[140:143], v[208:211], v[40:43]
	v_mfma_f32_16x16x32_bf16 v[28:31], v[132:135], v[216:219], v[28:31]
	v_mfma_f32_16x16x32_bf16 v[24:27], v[140:143], v[216:219], v[24:27]
	v_mfma_f32_16x16x32_bf16 v[12:15], v[132:135], v[224:227], v[12:15]
	v_mfma_f32_16x16x32_bf16 v[8:11], v[140:143], v[224:227], v[8:11]
	s_setprio 0
	s_setprio 1
	v_mfma_f32_16x16x32_bf16 v[52:55], v[144:147], v[192:195], v[52:55]
	v_mfma_f32_16x16x32_bf16 v[48:51], v[184:187], v[192:195], v[48:51]
	v_mfma_f32_16x16x32_bf16 v[36:39], v[144:147], v[204:207], v[36:39]
	v_mfma_f32_16x16x32_bf16 v[32:35], v[184:187], v[204:207], v[32:35]
	v_mfma_f32_16x16x32_bf16 v[20:23], v[144:147], v[212:215], v[20:23]
	v_mfma_f32_16x16x32_bf16 v[16:19], v[184:187], v[212:215], v[16:19]
	v_mfma_f32_16x16x32_bf16 v[4:7], v[144:147], v[220:223], v[4:7]
	v_mfma_f32_16x16x32_bf16 v[0:3], v[184:187], v[220:223], v[0:3]
	v_mfma_f32_16x16x32_bf16 v[52:55], v[148:151], v[196:199], v[52:55]
	v_mfma_f32_16x16x32_bf16 v[48:51], v[188:191], v[196:199], v[48:51]
	v_mfma_f32_16x16x32_bf16 v[36:39], v[148:151], v[208:211], v[36:39]
	v_mfma_f32_16x16x32_bf16 v[32:35], v[188:191], v[208:211], v[32:35]
	v_mfma_f32_16x16x32_bf16 v[20:23], v[148:151], v[216:219], v[20:23]
	v_mfma_f32_16x16x32_bf16 v[16:19], v[188:191], v[216:219], v[16:19]
	v_mfma_f32_16x16x32_bf16 v[4:7], v[148:151], v[224:227], v[4:7]
	v_mfma_f32_16x16x32_bf16 v[0:3], v[188:191], v[224:227], v[0:3]
	s_barrier
	s_setprio 0
	s_add_i32 s54, s54, 2
	s_add_u32 s20, s20, 0x100
	s_addc_u32 s21, s21, 0
	s_add_u32 s46, s46, 0x100
	s_addc_u32 s47, s47, 0
	s_cmp_gt_u32 s54, 41
	s_cbranch_scc0 .LBB0_372
	s_and_b64 vcc, exec, s[16:17]
	s_cbranch_vccz .LBB0_375
	s_barrier

; #define PG8_STAGE(bufoff, gbase, voff) do { _Pragma("unroll") for (int _i = 0; _i < 2; ++_i) \
;         __builtin_amdgcn_global_load_lds((const unsigned*)((const char*)(gbase) + (voff)[_i]), (PG8_LAS unsigned*)(lds + (bufoff) + ldsw + _i * 8192), 16, 0, 0); } while (0)
; #define PG8_LDA(dst, b, h) do { _Pragma("unroll") for (int m = 0; m < 4; ++m) _Pragma("unroll") for (int k = 0; k < 2; ++k) dst[m][k] = *(const PG8_LAS bf16x8*)(lds + PG8_SA(b, h) + aoff + m * 2048 + k * 1024); } while (0)
; #define PG8_LDB(dst, b, h) do { _Pragma("unroll") for (int n = 0; n < 2; ++n) _Pragma("unroll") for (int k = 0; k < 2; ++k) dst[n][k] = *(const PG8_LAS bf16x8*)(lds + PG8_SB(b, h) + boff + n * 2048 + k * 1024); } while (0)
; #define PG8_MMA(ai, bj, At, Bt) do { __builtin_amdgcn_s_setprio(1); _Pragma("unroll") for (int m = 0; m < 4; ++m) _Pragma("unroll") for (int n = 0; n < 2; ++n) _Pragma("unroll") for (int k = 0; k < 2; ++k) \
;         acc[ai][bj][m][n] = __builtin_amdgcn_mfma_f32_16x16x32_bf16(Bt[n][k], At[m][k], acc[ai][bj][m][n], 0, 0, 0); __builtin_amdgcn_s_setprio(0); } while (0)
; #define PG8_WAIT_V(n) asm volatile("s_waitcnt vmcnt(" #n ")" ::: "memory")
; #define PG8_WAIT_L(n) asm volatile("s_waitcnt lgkmcnt(" #n ")" ::: "memory")
; template <class Epi, class Sched, bool ALIGN_EPI = false, bool SP2 = false>
; __device__ __forceinline__ void gemm_phase(PG8_LAS unsigned char* lds, const Gemm g, const Sched& S, const Epi& E) {
;     ...
;             const bool last = (t == nt - 2);
;             const char* a1 = cA + (size_t)(t + 1) * kstep;
;             const char* a2 = last ? nA : cA + (size_t)(t + 2) * kstep; const char* b2 = last ? nB : cB + (size_t)(t + 2) * kstep;
;             const char* a3 = a2 + kstep; const char* b3 = b2 + kstep;
;             if (last && has_next) S.a_ready(nxt);
;             if constexpr (SP2) {
;             PG8_LDB(B0, 0, 0); PG8_LDB(B1, 0, 1); PG8_SCHED; PG8_LDA(At, 0, 0); PG8_STAGE(PG8_SA(1, 1), a1 + hstep, voffA);
;             PG8_WAIT_V(8); PG8_WAIT_L(0); PG8_BAR; PG8_MMA(0, 0, At, B0); PG8_MMA(0, 1, At, B1); PG8_BAR; PG8_SCHED;
;             PG8_LDA(At, 0, 1); PG8_STAGE(PG8_SB(0, 0), b2, voffB); PG8_STAGE(PG8_SB(0, 1), b2 + hstep, voffB); PG8_STAGE(PG8_SA(0, 0), a2, voffA);
;             PG8_WAIT_V(8); PG8_WAIT_L(0); PG8_BAR; PG8_MMA(1, 0, At, B0); PG8_MMA(1, 1, At, B1); PG8_BAR; PG8_SCHED;
.LBB0_464:
	ds_read_b128 v[128:131], v149
	ds_read_b128 v[132:135], v149 offset:1024
	ds_read_b128 v[140:143], v149 offset:2048
	ds_read_b128 v[176:179], v149 offset:3072
	ds_read_b128 v[180:183], v150
	ds_read_b128 v[184:187], v150 offset:1024
	ds_read_b128 v[188:191], v150 offset:2048
	ds_read_b128 v[192:195], v150 offset:3072
	s_add_u32 s30, s0, 0xfffc0080
	s_addc_u32 s31, s1, -1
	s_cmp_eq_u32 s81, 12
	s_cselect_b32 s35, s13, s31
	s_cselect_b32 s34, s21, s30
	s_cselect_b32 s31, s19, s80
	s_cselect_b32 s30, s58, s59
	v_lshl_add_u64 v[228:229], s[0:1], 0, v[136:137]
	s_add_i32 m0, s29, 0xc000
	ds_read_b128 v[196:199], v151
	ds_read_b128 v[200:203], v151 offset:1024
	ds_read_b128 v[204:207], v151 offset:2048
	ds_read_b128 v[208:211], v151 offset:3072
	ds_read_b128 v[212:215], v151 offset:4096
	ds_read_b128 v[216:219], v151 offset:5120
	ds_read_b128 v[220:223], v151 offset:6144
	ds_read_b128 v[224:227], v151 offset:7168
	global_load_lds_dwordx4 v[228:229], off
	v_lshl_add_u64 v[228:229], s[0:1], 0, v[138:139]
	s_add_i32 m0, s29, 0xe000
	s_nop 0
	global_load_lds_dwordx4 v[228:229], off
	s_waitcnt vmcnt(8)
	s_waitcnt lgkmcnt(0)
	s_setprio 1
	s_barrier
	v_mfma_f32_16x16x32_bf16 v[124:127], v[128:131], v[196:199], v[124:127]
	v_mfma_f32_16x16x32_bf16 v[120:123], v[140:143], v[196:199], v[120:123]
	v_mfma_f32_16x16x32_bf16 v[108:111], v[128:131], v[204:207], v[108:111]
	v_mfma_f32_16x16x32_bf16 v[104:107], v[140:143], v[204:207], v[104:107]
	v_mfma_f32_16x16x32_bf16 v[92:95], v[128:131], v[212:215], v[92:95]
	v_mfma_f32_16x16x32_bf16 v[88:91], v[140:143], v[212:215], v[88:91]
	v_mfma_f32_16x16x32_bf16 v[76:79], v[128:131], v[220:223], v[76:79]
	v_mfma_f32_16x16x32_bf16 v[72:75], v[140:143], v[220:223], v[72:75]
	v_mfma_f32_16x16x32_bf16 v[124:127], v[132:135], v[200:203], v[124:127]
	v_mfma_f32_16x16x32_bf16 v[120:123], v[176:179], v[200:203], v[120:123]
	v_mfma_f32_16x16x32_bf16 v[108:111], v[132:135], v[208:211], v[108:111]
	v_mfma_f32_16x16x32_bf16 v[104:107], v[176:179], v[208:211], v[104:107]
	v_mfma_f32_16x16x32_bf16 v[92:95], v[132:135], v[216:219], v[92:95]
	v_mfma_f32_16x16x32_bf16 v[88:91], v[176:179], v[216:219], v[88:91]
	v_mfma_f32_16x16x32_bf16 v[76:79], v[132:135], v[224:227], v[76:79]
	v_mfma_f32_16x16x32_bf16 v[72:75], v[176:179], v[224:227], v[72:75]
	s_setprio 0
	s_setprio 1
	v_mfma_f32_16x16x32_bf16 v[116:119], v[180:183], v[196:199], v[116:119]
	v_mfma_f32_16x16x32_bf16 v[112:115], v[188:191], v[196:199], v[112:115]
	v_mfma_f32_16x16x32_bf16 v[100:103], v[180:183], v[204:207], v[100:103]
	v_mfma_f32_16x16x32_bf16 v[96:99], v[188:191], v[204:207], v[96:99]
	v_mfma_f32_16x16x32_bf16 v[84:87], v[180:183], v[212:215], v[84:87]
	v_mfma_f32_16x16x32_bf16 v[80:83], v[188:191], v[212:215], v[80:83]
	v_mfma_f32_16x16x32_bf16 v[68:71], v[180:183], v[220:223], v[68:71]
	v_mfma_f32_16x16x32_bf16 v[64:67], v[188:191], v[220:223], v[64:67]
	v_mfma_f32_16x16x32_bf16 v[116:119], v[184:187], v[200:203], v[116:119]
	v_mfma_f32_16x16x32_bf16 v[112:115], v[192:195], v[200:203], v[112:115]
	v_mfma_f32_16x16x32_bf16 v[100:103], v[184:187], v[208:211], v[100:103]
	v_mfma_f32_16x16x32_bf16 v[96:99], v[192:195], v[208:211], v[96:99]
	v_mfma_f32_16x16x32_bf16 v[84:87], v[184:187], v[216:219], v[84:87]
	v_mfma_f32_16x16x32_bf16 v[80:83], v[192:195], v[216:219], v[80:83]
	v_mfma_f32_16x16x32_bf16 v[68:71], v[184:187], v[224:227], v[68:71]
	v_mfma_f32_16x16x32_bf16 v[64:67], v[192:195], v[224:227], v[64:67]
	s_barrier
	s_setprio 0
	s_add_i32 s82, s46, s3
	v_lshl_add_u64 v[228:229], s[30:31], 0, v[158:159]
	s_mov_b32 m0, s82
	ds_read_b128 v[196:199], v151 offset:16384
	ds_read_b128 v[200:203], v151 offset:17408
	ds_read_b128 v[204:207], v151 offset:18432
	ds_read_b128 v[208:211], v151 offset:19456
	ds_read_b128 v[212:215], v151 offset:20480
	ds_read_b128 v[216:219], v151 offset:21504
	ds_read_b128 v[220:223], v151 offset:22528
	ds_read_b128 v[224:227], v151 offset:23552
	global_load_lds_dwordx4 v[228:229], off
	s_add_i32 m0, s82, 0x2000
	s_add_u32 s82, s30, 0x40000
	v_lshl_add_u64 v[248:249], s[30:31], 0, v[162:163]
	s_addc_u32 s83, s31, 0
	s_add_i32 s84, s47, s3
	global_load_lds_dwordx4 v[248:249], off
	v_lshl_add_u64 v[250:251], s[82:83], 0, v[158:159]
	s_mov_b32 m0, s84
	v_lshl_add_u64 v[252:253], s[34:35], 0, v[160:161]
	global_load_lds_dwordx4 v[250:251], off
	v_lshl_add_u64 v[250:251], s[82:83], 0, v[162:163]
	s_add_i32 m0, s84, 0x2000
	s_nop 0
	global_load_lds_dwordx4 v[250:251], off
	v_lshl_add_u64 v[250:251], s[34:35], 0, v[156:157]
	s_mov_b32 m0, s29
	s_nop 0
	global_load_lds_dwordx4 v[250:251], off
	s_mov_b32 m0, s37
	s_nop 0
	global_load_lds_dwordx4 v[252:253], off
	s_waitcnt vmcnt(8)
	s_waitcnt lgkmcnt(0)
	s_setprio 1
	s_barrier
; #define PG8_STAGE(bufoff, gbase, voff) do { _Pragma("unroll") for (int _i = 0; _i < 2; ++_i) \
;         __builtin_amdgcn_global_load_lds((const unsigned*)((const char*)(gbase) + (voff)[_i]), (PG8_LAS unsigned*)(lds + (bufoff) + ldsw + _i * 8192), 16, 0, 0); } while (0)
; #define PG8_LDA(dst, b, h) do { _Pragma("unroll") for (int m = 0; m < 4; ++m) _Pragma("unroll") for (int k = 0; k < 2; ++k) dst[m][k] = *(const PG8_LAS bf16x8*)(lds + PG8_SA(b, h) + aoff + m * 2048 + k * 1024); } while (0)
; #define PG8_LDB(dst, b, h) do { _Pragma("unroll") for (int n = 0; n < 2; ++n) _Pragma("unroll") for (int k = 0; k < 2; ++k) dst[n][k] = *(const PG8_LAS bf16x8*)(lds + PG8_SB(b, h) + boff + n * 2048 + k * 1024); } while (0)
; #define PG8_MMA(ai, bj, At, Bt) do { __builtin_amdgcn_s_setprio(1); _Pragma("unroll") for (int m = 0; m < 4; ++m) _Pragma("unroll") for (int n = 0; n < 2; ++n) _Pragma("unroll") for (int k = 0; k < 2; ++k) \
;         acc[ai][bj][m][n] = __builtin_amdgcn_mfma_f32_16x16x32_bf16(Bt[n][k], At[m][k], acc[ai][bj][m][n], 0, 0, 0); __builtin_amdgcn_s_setprio(0); } while (0)
; #define PG8_WAIT_V(n) asm volatile("s_waitcnt vmcnt(" #n ")" ::: "memory")
; #define PG8_WAIT_L(n) asm volatile("s_waitcnt lgkmcnt(" #n ")" ::: "memory")
; #define PG8_BAR __builtin_amdgcn_s_barrier()
; #define PG8_SCHED __builtin_amdgcn_sched_barrier(0)
; template <class Epi, class Sched, bool ALIGN_EPI = false, bool SP2 = false>
; __device__ __forceinline__ void gemm_phase(PG8_LAS unsigned char* lds, const Gemm g, const Sched& S, const Epi& E) {
;     ...
;             PG8_WAIT_V(8); PG8_WAIT_L(0); PG8_BAR; PG8_MMA(1, 0, At, B0); PG8_MMA(1, 1, At, B1); PG8_BAR; PG8_SCHED;
;             PG8_LDB(B0, 1, 0); PG8_LDB(B1, 1, 1); PG8_SCHED; PG8_LDA(At, 1, 0); PG8_STAGE(PG8_SA(0, 1), a2 + hstep, voffA);
;             PG8_WAIT_V(8); PG8_WAIT_L(0); PG8_BAR; PG8_MMA(0, 0, At, B0); PG8_MMA(0, 1, At, B1); PG8_BAR; PG8_SCHED;
	v_mfma_f32_16x16x32_bf16 v[60:63], v[128:131], v[196:199], v[60:63]
	v_mfma_f32_16x16x32_bf16 v[56:59], v[140:143], v[196:199], v[56:59]
	v_mfma_f32_16x16x32_bf16 v[44:47], v[128:131], v[204:207], v[44:47]
	v_mfma_f32_16x16x32_bf16 v[40:43], v[140:143], v[204:207], v[40:43]
	v_mfma_f32_16x16x32_bf16 v[28:31], v[128:131], v[212:215], v[28:31]
	v_mfma_f32_16x16x32_bf16 v[24:27], v[140:143], v[212:215], v[24:27]
	v_mfma_f32_16x16x32_bf16 v[12:15], v[128:131], v[220:223], v[12:15]
	v_mfma_f32_16x16x32_bf16 v[8:11], v[140:143], v[220:223], v[8:11]
	v_mfma_f32_16x16x32_bf16 v[60:63], v[132:135], v[200:203], v[60:63]
	v_mfma_f32_16x16x32_bf16 v[56:59], v[176:179], v[200:203], v[56:59]
	v_mfma_f32_16x16x32_bf16 v[44:47], v[132:135], v[208:211], v[44:47]
	v_mfma_f32_16x16x32_bf16 v[40:43], v[176:179], v[208:211], v[40:43]
	v_mfma_f32_16x16x32_bf16 v[28:31], v[132:135], v[216:219], v[28:31]
	v_mfma_f32_16x16x32_bf16 v[24:27], v[176:179], v[216:219], v[24:27]
	v_mfma_f32_16x16x32_bf16 v[12:15], v[132:135], v[224:227], v[12:15]
	v_mfma_f32_16x16x32_bf16 v[8:11], v[176:179], v[224:227], v[8:11]
	s_setprio 0
	s_setprio 1
	v_mfma_f32_16x16x32_bf16 v[52:55], v[180:183], v[196:199], v[52:55]
	v_mfma_f32_16x16x32_bf16 v[48:51], v[188:191], v[196:199], v[48:51]
	v_mfma_f32_16x16x32_bf16 v[36:39], v[180:183], v[204:207], v[36:39]
	v_mfma_f32_16x16x32_bf16 v[32:35], v[188:191], v[204:207], v[32:35]
	v_mfma_f32_16x16x32_bf16 v[20:23], v[180:183], v[212:215], v[20:23]
	v_mfma_f32_16x16x32_bf16 v[16:19], v[188:191], v[212:215], v[16:19]
	v_mfma_f32_16x16x32_bf16 v[4:7], v[180:183], v[220:223], v[4:7]
	v_mfma_f32_16x16x32_bf16 v[0:3], v[188:191], v[220:223], v[0:3]
	v_mfma_f32_16x16x32_bf16 v[52:55], v[184:187], v[200:203], v[52:55]
	v_mfma_f32_16x16x32_bf16 v[48:51], v[192:195], v[200:203], v[48:51]
	v_mfma_f32_16x16x32_bf16 v[36:39], v[184:187], v[208:211], v[36:39]
	v_mfma_f32_16x16x32_bf16 v[32:35], v[192:195], v[208:211], v[32:35]
	v_mfma_f32_16x16x32_bf16 v[20:23], v[184:187], v[216:219], v[20:23]
	v_mfma_f32_16x16x32_bf16 v[16:19], v[192:195], v[216:219], v[16:19]
	v_mfma_f32_16x16x32_bf16 v[4:7], v[184:187], v[224:227], v[4:7]
	v_mfma_f32_16x16x32_bf16 v[0:3], v[192:195], v[224:227], v[0:3]
	s_barrier
	s_setprio 0
	s_add_i32 s82, 0, 0x18000
	v_add_u32_e32 v144, s82, v146
	s_add_i32 s83, 0, 0x1c000
	ds_read_b128 v[128:131], v144
	ds_read_b128 v[132:135], v144 offset:1024
	ds_read_b128 v[140:143], v144 offset:2048
	ds_read_b128 v[176:179], v144 offset:3072
	v_add_u32_e32 v144, s83, v146
	ds_read_b128 v[180:183], v144
	ds_read_b128 v[184:187], v144 offset:1024
	ds_read_b128 v[188:191], v144 offset:2048
	ds_read_b128 v[192:195], v144 offset:3072
	s_add_u32 s34, s34, 0x40000
	s_addc_u32 s35, s35, 0
	s_mov_b32 m0, s38
	v_lshl_add_u64 v[238:239], s[34:35], 0, v[156:157]
	ds_read_b128 v[196:199], v151 offset:32768
	ds_read_b128 v[200:203], v151 offset:33792
	ds_read_b128 v[204:207], v151 offset:34816
	ds_read_b128 v[208:211], v151 offset:35840
	ds_read_b128 v[212:215], v151 offset:36864
	ds_read_b128 v[216:219], v151 offset:37888
	ds_read_b128 v[220:223], v151 offset:38912
	ds_read_b128 v[224:227], v151 offset:39936
	global_load_lds_dwordx4 v[238:239], off
	v_lshl_add_u64 v[238:239], s[34:35], 0, v[160:161]
	s_mov_b32 m0, s39
	s_nop 0
	global_load_lds_dwordx4 v[238:239], off
	s_waitcnt vmcnt(8)
	s_waitcnt lgkmcnt(0)
	s_setprio 1
	s_barrier
	v_mfma_f32_16x16x32_bf16 v[124:127], v[128:131], v[196:199], v[124:127]
	v_mfma_f32_16x16x32_bf16 v[120:123], v[140:143], v[196:199], v[120:123]
	v_mfma_f32_16x16x32_bf16 v[108:111], v[128:131], v[204:207], v[108:111]
	v_mfma_f32_16x16x32_bf16 v[104:107], v[140:143], v[204:207], v[104:107]
	v_mfma_f32_16x16x32_bf16 v[92:95], v[128:131], v[212:215], v[92:95]
	v_mfma_f32_16x16x32_bf16 v[88:91], v[140:143], v[212:215], v[88:91]
	v_mfma_f32_16x16x32_bf16 v[76:79], v[128:131], v[220:223], v[76:79]
	v_mfma_f32_16x16x32_bf16 v[72:75], v[140:143], v[220:223], v[72:75]
	v_mfma_f32_16x16x32_bf16 v[124:127], v[132:135], v[200:203], v[124:127]
	v_mfma_f32_16x16x32_bf16 v[120:123], v[176:179], v[200:203], v[120:123]
	v_mfma_f32_16x16x32_bf16 v[108:111], v[132:135], v[208:211], v[108:111]
	v_mfma_f32_16x16x32_bf16 v[104:107], v[176:179], v[208:211], v[104:107]
	v_mfma_f32_16x16x32_bf16 v[92:95], v[132:135], v[216:219], v[92:95]
	v_mfma_f32_16x16x32_bf16 v[88:91], v[176:179], v[216:219], v[88:91]
	v_mfma_f32_16x16x32_bf16 v[76:79], v[132:135], v[224:227], v[76:79]
	v_mfma_f32_16x16x32_bf16 v[72:75], v[176:179], v[224:227], v[72:75]
	s_setprio 0
	s_setprio 1
	v_mfma_f32_16x16x32_bf16 v[116:119], v[180:183], v[196:199], v[116:119]
	v_mfma_f32_16x16x32_bf16 v[112:115], v[188:191], v[196:199], v[112:115]
	v_mfma_f32_16x16x32_bf16 v[100:103], v[180:183], v[204:207], v[100:103]
	v_mfma_f32_16x16x32_bf16 v[96:99], v[188:191], v[204:207], v[96:99]
	v_mfma_f32_16x16x32_bf16 v[84:87], v[180:183], v[212:215], v[84:87]
	v_mfma_f32_16x16x32_bf16 v[80:83], v[188:191], v[212:215], v[80:83]
	v_mfma_f32_16x16x32_bf16 v[68:71], v[180:183], v[220:223], v[68:71]
	v_mfma_f32_16x16x32_bf16 v[64:67], v[188:191], v[220:223], v[64:67]
	v_mfma_f32_16x16x32_bf16 v[116:119], v[184:187], v[200:203], v[116:119]
	v_mfma_f32_16x16x32_bf16 v[112:115], v[192:195], v[200:203], v[112:115]
	v_mfma_f32_16x16x32_bf16 v[100:103], v[184:187], v[208:211], v[100:103]
	v_mfma_f32_16x16x32_bf16 v[96:99], v[192:195], v[208:211], v[96:99]
	v_mfma_f32_16x16x32_bf16 v[84:87], v[184:187], v[216:219], v[84:87]
	v_mfma_f32_16x16x32_bf16 v[80:83], v[192:195], v[216:219], v[80:83]
	v_mfma_f32_16x16x32_bf16 v[68:71], v[184:187], v[224:227], v[68:71]
	v_mfma_f32_16x16x32_bf16 v[64:67], v[192:195], v[224:227], v[64:67]
	s_barrier
; #define PG8_STAGE(bufoff, gbase, voff) do { _Pragma("unroll") for (int _i = 0; _i < 2; ++_i) \
;         __builtin_amdgcn_global_load_lds((const unsigned*)((const char*)(gbase) + (voff)[_i]), (PG8_LAS unsigned*)(lds + (bufoff) + ldsw + _i * 8192), 16, 0, 0); } while (0)
; #define PG8_LDA(dst, b, h) do { _Pragma("unroll") for (int m = 0; m < 4; ++m) _Pragma("unroll") for (int k = 0; k < 2; ++k) dst[m][k] = *(const PG8_LAS bf16x8*)(lds + PG8_SA(b, h) + aoff + m * 2048 + k * 1024); } while (0)
; #define PG8_MMA(ai, bj, At, Bt) do { __builtin_amdgcn_s_setprio(1); _Pragma("unroll") for (int m = 0; m < 4; ++m) _Pragma("unroll") for (int n = 0; n < 2; ++n) _Pragma("unroll") for (int k = 0; k < 2; ++k) \
;         acc[ai][bj][m][n] = __builtin_amdgcn_mfma_f32_16x16x32_bf16(Bt[n][k], At[m][k], acc[ai][bj][m][n], 0, 0, 0); __builtin_amdgcn_s_setprio(0); } while (0)
; #define PG8_WAIT_V(n) asm volatile("s_waitcnt vmcnt(" #n ")" ::: "memory")
; #define PG8_WAIT_L(n) asm volatile("s_waitcnt lgkmcnt(" #n ")" ::: "memory")
; #define PG8_BAR __builtin_amdgcn_s_barrier()
; #define PG8_SCHED __builtin_amdgcn_sched_barrier(0)
; template <class Epi, class Sched, bool ALIGN_EPI = false, bool SP2 = false>
; __device__ __forceinline__ void gemm_phase(PG8_LAS unsigned char* lds, const Gemm g, const Sched& S, const Epi& E) {
;     ...
;             PG8_LDA(At, 1, 1); PG8_STAGE(PG8_SB(1, 0), b3, voffB); PG8_STAGE(PG8_SB(1, 1), b3 + hstep, voffB); PG8_STAGE(PG8_SA(1, 0), a3, voffA);
;             PG8_WAIT_V(8); PG8_WAIT_L(0); PG8_BAR; PG8_MMA(1, 0, At, B0); PG8_MMA(1, 1, At, B1); PG8_BAR; PG8_SCHED;
;     ...
;         if constexpr (ALIGN_EPI) { if (wr == 0) PG8_BAR; }
	s_setprio 0
	s_add_i32 s34, s82, s3
	v_lshl_add_u64 v[228:229], v[228:229], 0, s[6:7]
	s_mov_b32 m0, s34
	ds_read_b128 v[196:199], v151 offset:49152
	ds_read_b128 v[200:203], v151 offset:50176
	ds_read_b128 v[204:207], v151 offset:51200
	ds_read_b128 v[208:211], v151 offset:52224
	ds_read_b128 v[212:215], v151 offset:53248
	ds_read_b128 v[216:219], v151 offset:54272
	ds_read_b128 v[220:223], v151 offset:55296
	ds_read_b128 v[224:227], v151 offset:56320
	global_load_lds_dwordx4 v[228:229], off
	s_add_i32 m0, s34, 0x2000
	s_add_u32 s30, s30, 0x40080
	v_lshl_add_u64 v[228:229], v[248:249], 0, s[6:7]
	s_addc_u32 s31, s31, 0
	s_add_i32 s34, s83, s3
	global_load_lds_dwordx4 v[228:229], off
	v_lshl_add_u64 v[228:229], s[30:31], 0, v[158:159]
	s_mov_b32 m0, s34
	s_nop 0
	global_load_lds_dwordx4 v[228:229], off
	v_lshl_add_u64 v[228:229], s[30:31], 0, v[162:163]
	s_add_i32 m0, s34, 0x2000
	s_nop 0
	global_load_lds_dwordx4 v[228:229], off
	v_lshl_add_u64 v[228:229], v[250:251], 0, s[6:7]
	s_mov_b32 m0, s41
	s_nop 0
	global_load_lds_dwordx4 v[228:229], off
	v_lshl_add_u64 v[228:229], v[252:253], 0, s[6:7]
	s_mov_b32 m0, s42
	s_nop 0
	global_load_lds_dwordx4 v[228:229], off
	s_waitcnt vmcnt(8)
	s_waitcnt lgkmcnt(0)
	s_setprio 1
	s_barrier
	v_mfma_f32_16x16x32_bf16 v[60:63], v[128:131], v[196:199], v[60:63]
	v_mfma_f32_16x16x32_bf16 v[56:59], v[140:143], v[196:199], v[56:59]
	v_mfma_f32_16x16x32_bf16 v[44:47], v[128:131], v[204:207], v[44:47]
	v_mfma_f32_16x16x32_bf16 v[40:43], v[140:143], v[204:207], v[40:43]
	v_mfma_f32_16x16x32_bf16 v[28:31], v[128:131], v[212:215], v[28:31]
	v_mfma_f32_16x16x32_bf16 v[24:27], v[140:143], v[212:215], v[24:27]
	v_mfma_f32_16x16x32_bf16 v[12:15], v[128:131], v[220:223], v[12:15]
	v_mfma_f32_16x16x32_bf16 v[8:11], v[140:143], v[220:223], v[8:11]
	v_mfma_f32_16x16x32_bf16 v[60:63], v[132:135], v[200:203], v[60:63]
	v_mfma_f32_16x16x32_bf16 v[56:59], v[176:179], v[200:203], v[56:59]
	v_mfma_f32_16x16x32_bf16 v[44:47], v[132:135], v[208:211], v[44:47]
	v_mfma_f32_16x16x32_bf16 v[40:43], v[176:179], v[208:211], v[40:43]
	v_mfma_f32_16x16x32_bf16 v[28:31], v[132:135], v[216:219], v[28:31]
	v_mfma_f32_16x16x32_bf16 v[24:27], v[176:179], v[216:219], v[24:27]
	v_mfma_f32_16x16x32_bf16 v[12:15], v[132:135], v[224:227], v[12:15]
	v_mfma_f32_16x16x32_bf16 v[8:11], v[176:179], v[224:227], v[8:11]
	s_setprio 0
	s_setprio 1
	v_mfma_f32_16x16x32_bf16 v[52:55], v[180:183], v[196:199], v[52:55]
	v_mfma_f32_16x16x32_bf16 v[48:51], v[188:191], v[196:199], v[48:51]
	v_mfma_f32_16x16x32_bf16 v[36:39], v[180:183], v[204:207], v[36:39]
	v_mfma_f32_16x16x32_bf16 v[32:35], v[188:191], v[204:207], v[32:35]
	v_mfma_f32_16x16x32_bf16 v[20:23], v[180:183], v[212:215], v[20:23]
	v_mfma_f32_16x16x32_bf16 v[16:19], v[188:191], v[212:215], v[16:19]
	v_mfma_f32_16x16x32_bf16 v[4:7], v[180:183], v[220:223], v[4:7]
	v_mfma_f32_16x16x32_bf16 v[0:3], v[188:191], v[220:223], v[0:3]
	v_mfma_f32_16x16x32_bf16 v[52:55], v[184:187], v[200:203], v[52:55]
	v_mfma_f32_16x16x32_bf16 v[48:51], v[192:195], v[200:203], v[48:51]
	v_mfma_f32_16x16x32_bf16 v[36:39], v[184:187], v[208:211], v[36:39]
	v_mfma_f32_16x16x32_bf16 v[32:35], v[192:195], v[208:211], v[32:35]
	v_mfma_f32_16x16x32_bf16 v[20:23], v[184:187], v[216:219], v[20:23]
	v_mfma_f32_16x16x32_bf16 v[16:19], v[192:195], v[216:219], v[16:19]
	v_mfma_f32_16x16x32_bf16 v[4:7], v[184:187], v[224:227], v[4:7]
	v_mfma_f32_16x16x32_bf16 v[0:3], v[192:195], v[224:227], v[0:3]
	s_barrier
	s_setprio 0
	s_add_i32 s81, s81, 2
	s_add_u32 s0, s0, 0x100
	s_addc_u32 s1, s1, 0
	s_add_u32 s59, s59, 0x100
	s_addc_u32 s80, s80, 0
	s_cmp_gt_u32 s81, 13
	s_cbranch_scc0 .LBB0_464
	s_and_b64 vcc, exec, s[16:17]
	s_cbranch_vccz .LBB0_467
	s_barrier

; #define PG8_STAGE(bufoff, gbase, voff) do { _Pragma("unroll") for (int _i = 0; _i < 2; ++_i) \
;         __builtin_amdgcn_global_load_lds((const unsigned*)((const char*)(gbase) + (voff)[_i]), (PG8_LAS unsigned*)(lds + (bufoff) + ldsw + _i * 8192), 16, 0, 0); } while (0)
; #define PG8_LDA(dst, b, h) do { _Pragma("unroll") for (int m = 0; m < 4; ++m) _Pragma("unroll") for (int k = 0; k < 2; ++k) dst[m][k] = *(const PG8_LAS bf16x8*)(lds + PG8_SA(b, h) + aoff + m * 2048 + k * 1024); } while (0)
; #define PG8_LDB(dst, b, h) do { _Pragma("unroll") for (int n = 0; n < 2; ++n) _Pragma("unroll") for (int k = 0; k < 2; ++k) dst[n][k] = *(const PG8_LAS bf16x8*)(lds + PG8_SB(b, h) + boff + n * 2048 + k * 1024); } while (0)
; #define PG8_MMA(ai, bj, At, Bt) do { __builtin_amdgcn_s_setprio(1); _Pragma("unroll") for (int m = 0; m < 4; ++m) _Pragma("unroll") for (int n = 0; n < 2; ++n) _Pragma("unroll") for (int k = 0; k < 2; ++k) \
;         acc[ai][bj][m][n] = __builtin_amdgcn_mfma_f32_16x16x32_bf16(Bt[n][k], At[m][k], acc[ai][bj][m][n], 0, 0, 0); __builtin_amdgcn_s_setprio(0); } while (0)
; #define PG8_WAIT_V(n) asm volatile("s_waitcnt vmcnt(" #n ")" ::: "memory")
; #define PG8_WAIT_L(n) asm volatile("s_waitcnt lgkmcnt(" #n ")" ::: "memory")
; template <class Epi, class Sched, bool ALIGN_EPI = false, bool SP2 = false>
; __device__ __forceinline__ void gemm_phase(PG8_LAS unsigned char* lds, const Gemm g, const Sched& S, const Epi& E) {
;     ...
;             const bool last = (t == nt - 2);
;             const char* a1 = cA + (size_t)(t + 1) * kstep;
;             const char* a2 = last ? nA : cA + (size_t)(t + 2) * kstep; const char* b2 = last ? nB : cB + (size_t)(t + 2) * kstep;
;             const char* a3 = a2 + kstep; const char* b3 = b2 + kstep;
;             if (last && has_next) S.a_ready(nxt);
;             if constexpr (SP2) {
;             PG8_LDB(B0, 0, 0); PG8_LDB(B1, 0, 1); PG8_SCHED; PG8_LDA(At, 0, 0); PG8_STAGE(PG8_SA(1, 1), a1 + hstep, voffA);
;             PG8_WAIT_V(8); PG8_WAIT_L(0); PG8_BAR; PG8_MMA(0, 0, At, B0); PG8_MMA(0, 1, At, B1); PG8_BAR; PG8_SCHED;
;             PG8_LDA(At, 0, 1); PG8_STAGE(PG8_SB(0, 0), b2, voffB); PG8_STAGE(PG8_SB(0, 1), b2 + hstep, voffB); PG8_STAGE(PG8_SA(0, 0), a2, voffA);
;             PG8_WAIT_V(8); PG8_WAIT_L(0); PG8_BAR; PG8_MMA(1, 0, At, B0); PG8_MMA(1, 1, At, B1); PG8_BAR; PG8_SCHED;
.LBB0_1230:
	ds_read_b128 v[128:131], v200
	ds_read_b128 v[132:135], v200 offset:1024
	ds_read_b128 v[136:139], v200 offset:2048
	ds_read_b128 v[140:143], v200 offset:3072
	ds_read_b128 v[144:147], v201
	ds_read_b128 v[148:151], v201 offset:1024
	ds_read_b128 v[182:185], v201 offset:2048
	ds_read_b128 v[186:189], v201 offset:3072
	s_add_u32 s28, s26, 0xfffc0080
	s_addc_u32 s29, s27, -1
	s_cmp_eq_u32 s52, 12
	s_cselect_b32 s31, s19, s29
	s_cselect_b32 s30, s25, s28
	s_cselect_b32 s29, s17, s51
	s_cselect_b32 s28, s47, s50
	v_lshl_add_u64 v[198:199], s[26:27], 0, v[174:175]
	s_add_i32 m0, s34, 0xc000
	ds_read_b128 v[190:193], v202
	ds_read_b128 v[194:197], v202 offset:1024
	ds_read_b128 v[204:207], v202 offset:2048
	ds_read_b128 v[208:211], v202 offset:3072
	ds_read_b128 v[212:215], v202 offset:4096
	ds_read_b128 v[216:219], v202 offset:5120
	ds_read_b128 v[220:223], v202 offset:6144
	ds_read_b128 v[224:227], v202 offset:7168
	global_load_lds_dwordx4 v[198:199], off
	v_lshl_add_u64 v[198:199], s[26:27], 0, v[176:177]
	s_add_i32 m0, s34, 0xe000
	s_nop 0
	global_load_lds_dwordx4 v[198:199], off
	s_waitcnt vmcnt(8)
	s_waitcnt lgkmcnt(0)
	s_setprio 1
	s_barrier
	v_mfma_f32_16x16x32_bf16 v[124:127], v[128:131], v[190:193], v[124:127]
	v_mfma_f32_16x16x32_bf16 v[120:123], v[136:139], v[190:193], v[120:123]
	v_mfma_f32_16x16x32_bf16 v[108:111], v[128:131], v[204:207], v[108:111]
	v_mfma_f32_16x16x32_bf16 v[104:107], v[136:139], v[204:207], v[104:107]
	v_mfma_f32_16x16x32_bf16 v[92:95], v[128:131], v[212:215], v[92:95]
	v_mfma_f32_16x16x32_bf16 v[88:91], v[136:139], v[212:215], v[88:91]
	v_mfma_f32_16x16x32_bf16 v[76:79], v[128:131], v[220:223], v[76:79]
	v_mfma_f32_16x16x32_bf16 v[72:75], v[136:139], v[220:223], v[72:75]
	v_mfma_f32_16x16x32_bf16 v[124:127], v[132:135], v[194:197], v[124:127]
	v_mfma_f32_16x16x32_bf16 v[120:123], v[140:143], v[194:197], v[120:123]
	v_mfma_f32_16x16x32_bf16 v[108:111], v[132:135], v[208:211], v[108:111]
	v_mfma_f32_16x16x32_bf16 v[104:107], v[140:143], v[208:211], v[104:107]
	v_mfma_f32_16x16x32_bf16 v[92:95], v[132:135], v[216:219], v[92:95]
	v_mfma_f32_16x16x32_bf16 v[88:91], v[140:143], v[216:219], v[88:91]
	v_mfma_f32_16x16x32_bf16 v[76:79], v[132:135], v[224:227], v[76:79]
	v_mfma_f32_16x16x32_bf16 v[72:75], v[140:143], v[224:227], v[72:75]
	s_setprio 0
	s_setprio 1
	v_mfma_f32_16x16x32_bf16 v[116:119], v[144:147], v[190:193], v[116:119]
	v_mfma_f32_16x16x32_bf16 v[112:115], v[182:185], v[190:193], v[112:115]
	v_mfma_f32_16x16x32_bf16 v[100:103], v[144:147], v[204:207], v[100:103]
	v_mfma_f32_16x16x32_bf16 v[96:99], v[182:185], v[204:207], v[96:99]
	v_mfma_f32_16x16x32_bf16 v[84:87], v[144:147], v[212:215], v[84:87]
	v_mfma_f32_16x16x32_bf16 v[80:83], v[182:185], v[212:215], v[80:83]
	v_mfma_f32_16x16x32_bf16 v[68:71], v[144:147], v[220:223], v[68:71]
	v_mfma_f32_16x16x32_bf16 v[64:67], v[182:185], v[220:223], v[64:67]
	v_mfma_f32_16x16x32_bf16 v[116:119], v[148:151], v[194:197], v[116:119]
	v_mfma_f32_16x16x32_bf16 v[112:115], v[186:189], v[194:197], v[112:115]
	v_mfma_f32_16x16x32_bf16 v[100:103], v[148:151], v[208:211], v[100:103]
	v_mfma_f32_16x16x32_bf16 v[96:99], v[186:189], v[208:211], v[96:99]
	v_mfma_f32_16x16x32_bf16 v[84:87], v[148:151], v[216:219], v[84:87]
	v_mfma_f32_16x16x32_bf16 v[80:83], v[186:189], v[216:219], v[80:83]
	v_mfma_f32_16x16x32_bf16 v[68:71], v[148:151], v[224:227], v[68:71]
	v_mfma_f32_16x16x32_bf16 v[64:67], v[186:189], v[224:227], v[64:67]
	s_barrier
	s_setprio 0
	s_add_i32 s53, s44, s33
	v_lshl_add_u64 v[198:199], s[28:29], 0, v[158:159]
	s_mov_b32 m0, s53
	ds_read_b128 v[190:193], v202 offset:16384
	ds_read_b128 v[194:197], v202 offset:17408
	ds_read_b128 v[204:207], v202 offset:18432
	ds_read_b128 v[208:211], v202 offset:19456
	ds_read_b128 v[212:215], v202 offset:20480
	ds_read_b128 v[216:219], v202 offset:21504
	ds_read_b128 v[220:223], v202 offset:22528
	ds_read_b128 v[224:227], v202 offset:23552
	global_load_lds_dwordx4 v[198:199], off
	s_add_i32 m0, s53, 0x2000
	s_add_u32 s54, s28, 0x40000
	v_lshl_add_u64 v[228:229], s[28:29], 0, v[162:163]
	s_addc_u32 s55, s29, 0
	s_add_i32 s53, s45, s33
	global_load_lds_dwordx4 v[228:229], off
	v_lshl_add_u64 v[238:239], s[54:55], 0, v[158:159]
	s_mov_b32 m0, s53
	v_lshl_add_u64 v[246:247], s[30:31], 0, v[160:161]
	global_load_lds_dwordx4 v[238:239], off
	v_lshl_add_u64 v[238:239], s[54:55], 0, v[162:163]
	s_add_i32 m0, s53, 0x2000
	s_nop 0
	global_load_lds_dwordx4 v[238:239], off
	v_lshl_add_u64 v[238:239], s[30:31], 0, v[156:157]
	s_mov_b32 m0, s34
	s_nop 0
	global_load_lds_dwordx4 v[238:239], off
	s_mov_b32 m0, s35
	s_nop 0
	global_load_lds_dwordx4 v[246:247], off
	s_waitcnt vmcnt(8)
	s_waitcnt lgkmcnt(0)
	s_setprio 1
	s_barrier
; #define PG8_STAGE(bufoff, gbase, voff) do { _Pragma("unroll") for (int _i = 0; _i < 2; ++_i) \
;         __builtin_amdgcn_global_load_lds((const unsigned*)((const char*)(gbase) + (voff)[_i]), (PG8_LAS unsigned*)(lds + (bufoff) + ldsw + _i * 8192), 16, 0, 0); } while (0)
; #define PG8_LDA(dst, b, h) do { _Pragma("unroll") for (int m = 0; m < 4; ++m) _Pragma("unroll") for (int k = 0; k < 2; ++k) dst[m][k] = *(const PG8_LAS bf16x8*)(lds + PG8_SA(b, h) + aoff + m * 2048 + k * 1024); } while (0)
; #define PG8_LDB(dst, b, h) do { _Pragma("unroll") for (int n = 0; n < 2; ++n) _Pragma("unroll") for (int k = 0; k < 2; ++k) dst[n][k] = *(const PG8_LAS bf16x8*)(lds + PG8_SB(b, h) + boff + n * 2048 + k * 1024); } while (0)
; #define PG8_MMA(ai, bj, At, Bt) do { __builtin_amdgcn_s_setprio(1); _Pragma("unroll") for (int m = 0; m < 4; ++m) _Pragma("unroll") for (int n = 0; n < 2; ++n) _Pragma("unroll") for (int k = 0; k < 2; ++k) \
;         acc[ai][bj][m][n] = __builtin_amdgcn_mfma_f32_16x16x32_bf16(Bt[n][k], At[m][k], acc[ai][bj][m][n], 0, 0, 0); __builtin_amdgcn_s_setprio(0); } while (0)
; #define PG8_WAIT_V(n) asm volatile("s_waitcnt vmcnt(" #n ")" ::: "memory")
; #define PG8_WAIT_L(n) asm volatile("s_waitcnt lgkmcnt(" #n ")" ::: "memory")
; #define PG8_BAR __builtin_amdgcn_s_barrier()
; #define PG8_SCHED __builtin_amdgcn_sched_barrier(0)
; template <class Epi, class Sched, bool ALIGN_EPI = false, bool SP2 = false>
; __device__ __forceinline__ void gemm_phase(PG8_LAS unsigned char* lds, const Gemm g, const Sched& S, const Epi& E) {
;     ...
;             PG8_WAIT_V(8); PG8_WAIT_L(0); PG8_BAR; PG8_MMA(1, 0, At, B0); PG8_MMA(1, 1, At, B1); PG8_BAR; PG8_SCHED;
;             PG8_LDB(B0, 1, 0); PG8_LDB(B1, 1, 1); PG8_SCHED; PG8_LDA(At, 1, 0); PG8_STAGE(PG8_SA(0, 1), a2 + hstep, voffA);
;             PG8_WAIT_V(8); PG8_WAIT_L(0); PG8_BAR; PG8_MMA(0, 0, At, B0); PG8_MMA(0, 1, At, B1); PG8_BAR; PG8_SCHED;
	v_mfma_f32_16x16x32_bf16 v[60:63], v[128:131], v[190:193], v[60:63]
	v_mfma_f32_16x16x32_bf16 v[56:59], v[136:139], v[190:193], v[56:59]
	v_mfma_f32_16x16x32_bf16 v[44:47], v[128:131], v[204:207], v[44:47]
	v_mfma_f32_16x16x32_bf16 v[40:43], v[136:139], v[204:207], v[40:43]
	v_mfma_f32_16x16x32_bf16 v[28:31], v[128:131], v[212:215], v[28:31]
	v_mfma_f32_16x16x32_bf16 v[24:27], v[136:139], v[212:215], v[24:27]
	v_mfma_f32_16x16x32_bf16 v[12:15], v[128:131], v[220:223], v[12:15]
	v_mfma_f32_16x16x32_bf16 v[8:11], v[136:139], v[220:223], v[8:11]
	v_mfma_f32_16x16x32_bf16 v[60:63], v[132:135], v[194:197], v[60:63]
	v_mfma_f32_16x16x32_bf16 v[56:59], v[140:143], v[194:197], v[56:59]
	v_mfma_f32_16x16x32_bf16 v[44:47], v[132:135], v[208:211], v[44:47]
	v_mfma_f32_16x16x32_bf16 v[40:43], v[140:143], v[208:211], v[40:43]
	v_mfma_f32_16x16x32_bf16 v[28:31], v[132:135], v[216:219], v[28:31]
	v_mfma_f32_16x16x32_bf16 v[24:27], v[140:143], v[216:219], v[24:27]
	v_mfma_f32_16x16x32_bf16 v[12:15], v[132:135], v[224:227], v[12:15]
	v_mfma_f32_16x16x32_bf16 v[8:11], v[140:143], v[224:227], v[8:11]
	s_setprio 0
	s_setprio 1
	v_mfma_f32_16x16x32_bf16 v[52:55], v[144:147], v[190:193], v[52:55]
	v_mfma_f32_16x16x32_bf16 v[48:51], v[182:185], v[190:193], v[48:51]
	v_mfma_f32_16x16x32_bf16 v[36:39], v[144:147], v[204:207], v[36:39]
	v_mfma_f32_16x16x32_bf16 v[32:35], v[182:185], v[204:207], v[32:35]
	v_mfma_f32_16x16x32_bf16 v[20:23], v[144:147], v[212:215], v[20:23]
	v_mfma_f32_16x16x32_bf16 v[16:19], v[182:185], v[212:215], v[16:19]
	v_mfma_f32_16x16x32_bf16 v[4:7], v[144:147], v[220:223], v[4:7]
	v_mfma_f32_16x16x32_bf16 v[0:3], v[182:185], v[220:223], v[0:3]
	v_mfma_f32_16x16x32_bf16 v[52:55], v[148:151], v[194:197], v[52:55]
	v_mfma_f32_16x16x32_bf16 v[48:51], v[186:189], v[194:197], v[48:51]
	v_mfma_f32_16x16x32_bf16 v[36:39], v[148:151], v[208:211], v[36:39]
	v_mfma_f32_16x16x32_bf16 v[32:35], v[186:189], v[208:211], v[32:35]
	v_mfma_f32_16x16x32_bf16 v[20:23], v[148:151], v[216:219], v[20:23]
	v_mfma_f32_16x16x32_bf16 v[16:19], v[186:189], v[216:219], v[16:19]
	v_mfma_f32_16x16x32_bf16 v[4:7], v[148:151], v[224:227], v[4:7]
	v_mfma_f32_16x16x32_bf16 v[0:3], v[186:189], v[224:227], v[0:3]
	s_barrier
	s_setprio 0
	s_add_i32 s53, 0, 0x18000
	s_add_i32 s54, 0, 0x1c000
	v_add_u32_e32 v140, s53, v169
	v_add_u32_e32 v186, s54, v169
	ds_read_b128 v[128:131], v140
	ds_read_b128 v[132:135], v140 offset:1024
	ds_read_b128 v[136:139], v140 offset:2048
	ds_read_b128 v[140:143], v140 offset:3072
	ds_read_b128 v[144:147], v186
	ds_read_b128 v[148:151], v186 offset:1024
	ds_read_b128 v[182:185], v186 offset:2048
	ds_read_b128 v[186:189], v186 offset:3072
	s_add_u32 s30, s30, 0x40000
	s_addc_u32 s31, s31, 0
	s_mov_b32 m0, s36
	v_lshl_add_u64 v[248:249], s[30:31], 0, v[156:157]
	ds_read_b128 v[190:193], v202 offset:32768
	ds_read_b128 v[194:197], v202 offset:33792
	ds_read_b128 v[204:207], v202 offset:34816
	ds_read_b128 v[208:211], v202 offset:35840
	ds_read_b128 v[212:215], v202 offset:36864
	ds_read_b128 v[216:219], v202 offset:37888
	ds_read_b128 v[220:223], v202 offset:38912
	ds_read_b128 v[224:227], v202 offset:39936
	global_load_lds_dwordx4 v[248:249], off
	v_lshl_add_u64 v[248:249], s[30:31], 0, v[160:161]
	s_mov_b32 m0, s37
	s_nop 0
	global_load_lds_dwordx4 v[248:249], off
	s_waitcnt vmcnt(8)
	s_waitcnt lgkmcnt(0)
	s_setprio 1
	s_barrier
	v_mfma_f32_16x16x32_bf16 v[124:127], v[128:131], v[190:193], v[124:127]
	v_mfma_f32_16x16x32_bf16 v[120:123], v[136:139], v[190:193], v[120:123]
	v_mfma_f32_16x16x32_bf16 v[108:111], v[128:131], v[204:207], v[108:111]
	v_mfma_f32_16x16x32_bf16 v[104:107], v[136:139], v[204:207], v[104:107]
	v_mfma_f32_16x16x32_bf16 v[92:95], v[128:131], v[212:215], v[92:95]
	v_mfma_f32_16x16x32_bf16 v[88:91], v[136:139], v[212:215], v[88:91]
	v_mfma_f32_16x16x32_bf16 v[76:79], v[128:131], v[220:223], v[76:79]
	v_mfma_f32_16x16x32_bf16 v[72:75], v[136:139], v[220:223], v[72:75]
	v_mfma_f32_16x16x32_bf16 v[124:127], v[132:135], v[194:197], v[124:127]
	v_mfma_f32_16x16x32_bf16 v[120:123], v[140:143], v[194:197], v[120:123]
	v_mfma_f32_16x16x32_bf16 v[108:111], v[132:135], v[208:211], v[108:111]
	v_mfma_f32_16x16x32_bf16 v[104:107], v[140:143], v[208:211], v[104:107]
	v_mfma_f32_16x16x32_bf16 v[92:95], v[132:135], v[216:219], v[92:95]
	v_mfma_f32_16x16x32_bf16 v[88:91], v[140:143], v[216:219], v[88:91]
	v_mfma_f32_16x16x32_bf16 v[76:79], v[132:135], v[224:227], v[76:79]
	v_mfma_f32_16x16x32_bf16 v[72:75], v[140:143], v[224:227], v[72:75]
	s_setprio 0
	s_setprio 1
	v_mfma_f32_16x16x32_bf16 v[116:119], v[144:147], v[190:193], v[116:119]
	v_mfma_f32_16x16x32_bf16 v[112:115], v[182:185], v[190:193], v[112:115]
	v_mfma_f32_16x16x32_bf16 v[100:103], v[144:147], v[204:207], v[100:103]
	v_mfma_f32_16x16x32_bf16 v[96:99], v[182:185], v[204:207], v[96:99]
	v_mfma_f32_16x16x32_bf16 v[84:87], v[144:147], v[212:215], v[84:87]
	v_mfma_f32_16x16x32_bf16 v[80:83], v[182:185], v[212:215], v[80:83]
	v_mfma_f32_16x16x32_bf16 v[68:71], v[144:147], v[220:223], v[68:71]
	v_mfma_f32_16x16x32_bf16 v[64:67], v[182:185], v[220:223], v[64:67]
	v_mfma_f32_16x16x32_bf16 v[116:119], v[148:151], v[194:197], v[116:119]
	v_mfma_f32_16x16x32_bf16 v[112:115], v[186:189], v[194:197], v[112:115]
	v_mfma_f32_16x16x32_bf16 v[100:103], v[148:151], v[208:211], v[100:103]
	v_mfma_f32_16x16x32_bf16 v[96:99], v[186:189], v[208:211], v[96:99]
	v_mfma_f32_16x16x32_bf16 v[84:87], v[148:151], v[216:219], v[84:87]
	v_mfma_f32_16x16x32_bf16 v[80:83], v[186:189], v[216:219], v[80:83]
	v_mfma_f32_16x16x32_bf16 v[68:71], v[148:151], v[224:227], v[68:71]
	v_mfma_f32_16x16x32_bf16 v[64:67], v[186:189], v[224:227], v[64:67]
	s_barrier
; #define PG8_STAGE(bufoff, gbase, voff) do { _Pragma("unroll") for (int _i = 0; _i < 2; ++_i) \
;         __builtin_amdgcn_global_load_lds((const unsigned*)((const char*)(gbase) + (voff)[_i]), (PG8_LAS unsigned*)(lds + (bufoff) + ldsw + _i * 8192), 16, 0, 0); } while (0)
; #define PG8_LDA(dst, b, h) do { _Pragma("unroll") for (int m = 0; m < 4; ++m) _Pragma("unroll") for (int k = 0; k < 2; ++k) dst[m][k] = *(const PG8_LAS bf16x8*)(lds + PG8_SA(b, h) + aoff + m * 2048 + k * 1024); } while (0)
; #define PG8_MMA(ai, bj, At, Bt) do { __builtin_amdgcn_s_setprio(1); _Pragma("unroll") for (int m = 0; m < 4; ++m) _Pragma("unroll") for (int n = 0; n < 2; ++n) _Pragma("unroll") for (int k = 0; k < 2; ++k) \
;         acc[ai][bj][m][n] = __builtin_amdgcn_mfma_f32_16x16x32_bf16(Bt[n][k], At[m][k], acc[ai][bj][m][n], 0, 0, 0); __builtin_amdgcn_s_setprio(0); } while (0)
; #define PG8_WAIT_V(n) asm volatile("s_waitcnt vmcnt(" #n ")" ::: "memory")
; #define PG8_WAIT_L(n) asm volatile("s_waitcnt lgkmcnt(" #n ")" ::: "memory")
; #define PG8_BAR __builtin_amdgcn_s_barrier()
; #define PG8_SCHED __builtin_amdgcn_sched_barrier(0)
; template <class Epi, class Sched, bool ALIGN_EPI = false, bool SP2 = false>
; __device__ __forceinline__ void gemm_phase(PG8_LAS unsigned char* lds, const Gemm g, const Sched& S, const Epi& E) {
;     ...
;             PG8_LDA(At, 1, 1); PG8_STAGE(PG8_SB(1, 0), b3, voffB); PG8_STAGE(PG8_SB(1, 1), b3 + hstep, voffB); PG8_STAGE(PG8_SA(1, 0), a3, voffA);
;             PG8_WAIT_V(8); PG8_WAIT_L(0); PG8_BAR; PG8_MMA(1, 0, At, B0); PG8_MMA(1, 1, At, B1); PG8_BAR; PG8_SCHED;
;     ...
;         if constexpr (ALIGN_EPI) { if (wr == 0) PG8_BAR; }
	s_setprio 0
	s_add_i32 s30, s53, s33
	v_lshl_add_u64 v[198:199], v[198:199], 0, s[6:7]
	s_mov_b32 m0, s30
	ds_read_b128 v[190:193], v202 offset:49152
	ds_read_b128 v[194:197], v202 offset:50176
	ds_read_b128 v[204:207], v202 offset:51200
	ds_read_b128 v[208:211], v202 offset:52224
	ds_read_b128 v[212:215], v202 offset:53248
	ds_read_b128 v[216:219], v202 offset:54272
	ds_read_b128 v[220:223], v202 offset:55296
	ds_read_b128 v[224:227], v202 offset:56320
	global_load_lds_dwordx4 v[198:199], off
	s_add_i32 m0, s30, 0x2000
	s_add_u32 s28, s28, 0x40080
	v_lshl_add_u64 v[198:199], v[228:229], 0, s[6:7]
	s_addc_u32 s29, s29, 0
	s_add_i32 s30, s54, s33
	global_load_lds_dwordx4 v[198:199], off
	v_lshl_add_u64 v[198:199], s[28:29], 0, v[158:159]
	s_mov_b32 m0, s30
	s_nop 0
	global_load_lds_dwordx4 v[198:199], off
	v_lshl_add_u64 v[198:199], s[28:29], 0, v[162:163]
	s_add_i32 m0, s30, 0x2000
	s_nop 0
	global_load_lds_dwordx4 v[198:199], off
	v_lshl_add_u64 v[198:199], v[238:239], 0, s[6:7]
	s_mov_b32 m0, s39
	s_nop 0
	global_load_lds_dwordx4 v[198:199], off
	v_lshl_add_u64 v[198:199], v[246:247], 0, s[6:7]
	s_mov_b32 m0, s40
	s_nop 0
	global_load_lds_dwordx4 v[198:199], off
	s_waitcnt vmcnt(8)
	s_waitcnt lgkmcnt(0)
	s_setprio 1
	s_barrier
	v_mfma_f32_16x16x32_bf16 v[60:63], v[128:131], v[190:193], v[60:63]
	v_mfma_f32_16x16x32_bf16 v[56:59], v[136:139], v[190:193], v[56:59]
	v_mfma_f32_16x16x32_bf16 v[44:47], v[128:131], v[204:207], v[44:47]
	v_mfma_f32_16x16x32_bf16 v[40:43], v[136:139], v[204:207], v[40:43]
	v_mfma_f32_16x16x32_bf16 v[28:31], v[128:131], v[212:215], v[28:31]
	v_mfma_f32_16x16x32_bf16 v[24:27], v[136:139], v[212:215], v[24:27]
	v_mfma_f32_16x16x32_bf16 v[12:15], v[128:131], v[220:223], v[12:15]
	v_mfma_f32_16x16x32_bf16 v[8:11], v[136:139], v[220:223], v[8:11]
	v_mfma_f32_16x16x32_bf16 v[60:63], v[132:135], v[194:197], v[60:63]
	v_mfma_f32_16x16x32_bf16 v[56:59], v[140:143], v[194:197], v[56:59]
	v_mfma_f32_16x16x32_bf16 v[44:47], v[132:135], v[208:211], v[44:47]
	v_mfma_f32_16x16x32_bf16 v[40:43], v[140:143], v[208:211], v[40:43]
	v_mfma_f32_16x16x32_bf16 v[28:31], v[132:135], v[216:219], v[28:31]
	v_mfma_f32_16x16x32_bf16 v[24:27], v[140:143], v[216:219], v[24:27]
	v_mfma_f32_16x16x32_bf16 v[12:15], v[132:135], v[224:227], v[12:15]
	v_mfma_f32_16x16x32_bf16 v[8:11], v[140:143], v[224:227], v[8:11]
	s_setprio 0
	s_setprio 1
	v_mfma_f32_16x16x32_bf16 v[52:55], v[144:147], v[190:193], v[52:55]
	v_mfma_f32_16x16x32_bf16 v[48:51], v[182:185], v[190:193], v[48:51]
	v_mfma_f32_16x16x32_bf16 v[36:39], v[144:147], v[204:207], v[36:39]
	v_mfma_f32_16x16x32_bf16 v[32:35], v[182:185], v[204:207], v[32:35]
	v_mfma_f32_16x16x32_bf16 v[20:23], v[144:147], v[212:215], v[20:23]
	v_mfma_f32_16x16x32_bf16 v[16:19], v[182:185], v[212:215], v[16:19]
	v_mfma_f32_16x16x32_bf16 v[4:7], v[144:147], v[220:223], v[4:7]
	v_mfma_f32_16x16x32_bf16 v[0:3], v[182:185], v[220:223], v[0:3]
	v_mfma_f32_16x16x32_bf16 v[52:55], v[148:151], v[194:197], v[52:55]
	v_mfma_f32_16x16x32_bf16 v[48:51], v[186:189], v[194:197], v[48:51]
	v_mfma_f32_16x16x32_bf16 v[36:39], v[148:151], v[208:211], v[36:39]
	v_mfma_f32_16x16x32_bf16 v[32:35], v[186:189], v[208:211], v[32:35]
	v_mfma_f32_16x16x32_bf16 v[20:23], v[148:151], v[216:219], v[20:23]
	v_mfma_f32_16x16x32_bf16 v[16:19], v[186:189], v[216:219], v[16:19]
	v_mfma_f32_16x16x32_bf16 v[4:7], v[148:151], v[224:227], v[4:7]
	v_mfma_f32_16x16x32_bf16 v[0:3], v[186:189], v[224:227], v[0:3]
	s_barrier
	s_setprio 0
	s_add_i32 s52, s52, 2
	s_add_u32 s26, s26, 0x100
	s_addc_u32 s27, s27, 0
	s_add_u32 s50, s50, 0x100
	s_addc_u32 s51, s51, 0
	s_cmp_gt_u32 s52, 13
	s_cbranch_scc0 .LBB0_1230
	s_and_b64 vcc, exec, s[14:15]
	s_cbranch_vccz .LBB0_1233
	s_barrier

; #define PG8_STAGE(bufoff, gbase, voff) do { _Pragma("unroll") for (int _i = 0; _i < 2; ++_i) \
;         __builtin_amdgcn_global_load_lds((const unsigned*)((const char*)(gbase) + (voff)[_i]), (PG8_LAS unsigned*)(lds + (bufoff) + ldsw + _i * 8192), 16, 0, 0); } while (0)
; #define PG8_LDA(dst, b, h) do { _Pragma("unroll") for (int m = 0; m < 4; ++m) _Pragma("unroll") for (int k = 0; k < 2; ++k) dst[m][k] = *(const PG8_LAS bf16x8*)(lds + PG8_SA(b, h) + aoff + m * 2048 + k * 1024); } while (0)
; #define PG8_LDB(dst, b, h) do { _Pragma("unroll") for (int n = 0; n < 2; ++n) _Pragma("unroll") for (int k = 0; k < 2; ++k) dst[n][k] = *(const PG8_LAS bf16x8*)(lds + PG8_SB(b, h) + boff + n * 2048 + k * 1024); } while (0)
; #define PG8_MMA(ai, bj, At, Bt) do { __builtin_amdgcn_s_setprio(1); _Pragma("unroll") for (int m = 0; m < 4; ++m) _Pragma("unroll") for (int n = 0; n < 2; ++n) _Pragma("unroll") for (int k = 0; k < 2; ++k) \
;         acc[ai][bj][m][n] = __builtin_amdgcn_mfma_f32_16x16x32_bf16(Bt[n][k], At[m][k], acc[ai][bj][m][n], 0, 0, 0); __builtin_amdgcn_s_setprio(0); } while (0)
; #define PG8_WAIT_V(n) asm volatile("s_waitcnt vmcnt(" #n ")" ::: "memory")
; #define PG8_WAIT_L(n) asm volatile("s_waitcnt lgkmcnt(" #n ")" ::: "memory")
; template <class Epi, class Sched, bool ALIGN_EPI = false, bool SP2 = false>
; __device__ __forceinline__ void gemm_phase(PG8_LAS unsigned char* lds, const Gemm g, const Sched& S, const Epi& E) {
;     ...
;             const bool last = (t == nt - 2);
;             const char* a1 = cA + (size_t)(t + 1) * kstep;
;             const char* a2 = last ? nA : cA + (size_t)(t + 2) * kstep; const char* b2 = last ? nB : cB + (size_t)(t + 2) * kstep;
;             const char* a3 = a2 + kstep; const char* b3 = b2 + kstep;
;             if (last && has_next) S.a_ready(nxt);
;             if constexpr (SP2) {
;             PG8_LDB(B0, 0, 0); PG8_LDB(B1, 0, 1); PG8_SCHED; PG8_LDA(At, 0, 0); PG8_STAGE(PG8_SA(1, 1), a1 + hstep, voffA);
;             PG8_WAIT_V(8); PG8_WAIT_L(0); PG8_BAR; PG8_MMA(0, 0, At, B0); PG8_MMA(0, 1, At, B1); PG8_BAR; PG8_SCHED;
;             PG8_LDA(At, 0, 1); PG8_STAGE(PG8_SB(0, 0), b2, voffB); PG8_STAGE(PG8_SB(0, 1), b2 + hstep, voffB); PG8_STAGE(PG8_SA(0, 0), a2, voffA);
;             PG8_WAIT_V(8); PG8_WAIT_L(0); PG8_BAR; PG8_MMA(1, 0, At, B0); PG8_MMA(1, 1, At, B1); PG8_BAR; PG8_SCHED;
.LBB0_1322:
	ds_read_b128 v[136:139], v144
	ds_read_b128 v[174:177], v144 offset:1024
	ds_read_b128 v[178:181], v144 offset:2048
	ds_read_b128 v[182:185], v144 offset:3072
	ds_read_b128 v[186:189], v145
	ds_read_b128 v[190:193], v145 offset:1024
	ds_read_b128 v[194:197], v145 offset:2048
	ds_read_b128 v[198:201], v145 offset:3072
	s_add_u32 s26, s24, 0xfffc0080
	s_addc_u32 s27, s25, -1
	s_cmp_eq_u32 s50, 12
	s_cselect_b32 s29, s1, s27
	s_cselect_b32 s28, s11, s26
	s_cselect_b32 s27, s17, s49
	s_cselect_b32 s26, s19, s48
	v_lshl_add_u64 v[150:151], s[24:25], 0, v[128:129]
	s_add_i32 m0, s33, 0xc000
	ds_read_b128 v[202:205], v146
	ds_read_b128 v[206:209], v146 offset:1024
	ds_read_b128 v[210:213], v146 offset:2048
	ds_read_b128 v[214:217], v146 offset:3072
	ds_read_b128 v[218:221], v146 offset:4096
	ds_read_b128 v[222:225], v146 offset:5120
	ds_read_b128 v[226:229], v146 offset:6144
	ds_read_b128 v[236:239], v146 offset:7168
	global_load_lds_dwordx4 v[150:151], off
	v_lshl_add_u64 v[150:151], s[24:25], 0, v[130:131]
	s_add_i32 m0, s33, 0xe000
	s_nop 0
	global_load_lds_dwordx4 v[150:151], off
	s_waitcnt vmcnt(8)
	s_waitcnt lgkmcnt(0)
	s_setprio 1
	s_barrier
	v_mfma_f32_16x16x32_bf16 v[124:127], v[136:139], v[202:205], v[124:127]
	v_mfma_f32_16x16x32_bf16 v[116:119], v[178:181], v[202:205], v[116:119]
	v_mfma_f32_16x16x32_bf16 v[108:111], v[136:139], v[210:213], v[108:111]
	v_mfma_f32_16x16x32_bf16 v[100:103], v[178:181], v[210:213], v[100:103]
	v_mfma_f32_16x16x32_bf16 v[92:95], v[136:139], v[218:221], v[92:95]
	v_mfma_f32_16x16x32_bf16 v[84:87], v[178:181], v[218:221], v[84:87]
	v_mfma_f32_16x16x32_bf16 v[76:79], v[136:139], v[226:229], v[76:79]
	v_mfma_f32_16x16x32_bf16 v[68:71], v[178:181], v[226:229], v[68:71]
	v_mfma_f32_16x16x32_bf16 v[124:127], v[174:177], v[206:209], v[124:127]
	v_mfma_f32_16x16x32_bf16 v[116:119], v[182:185], v[206:209], v[116:119]
	v_mfma_f32_16x16x32_bf16 v[108:111], v[174:177], v[214:217], v[108:111]
	v_mfma_f32_16x16x32_bf16 v[100:103], v[182:185], v[214:217], v[100:103]
	v_mfma_f32_16x16x32_bf16 v[92:95], v[174:177], v[222:225], v[92:95]
	v_mfma_f32_16x16x32_bf16 v[84:87], v[182:185], v[222:225], v[84:87]
	v_mfma_f32_16x16x32_bf16 v[76:79], v[174:177], v[236:239], v[76:79]
	v_mfma_f32_16x16x32_bf16 v[68:71], v[182:185], v[236:239], v[68:71]
	s_setprio 0
	s_setprio 1
	v_mfma_f32_16x16x32_bf16 v[120:123], v[186:189], v[202:205], v[120:123]
	v_mfma_f32_16x16x32_bf16 v[112:115], v[194:197], v[202:205], v[112:115]
	v_mfma_f32_16x16x32_bf16 v[104:107], v[186:189], v[210:213], v[104:107]
	v_mfma_f32_16x16x32_bf16 v[96:99], v[194:197], v[210:213], v[96:99]
	v_mfma_f32_16x16x32_bf16 v[88:91], v[186:189], v[218:221], v[88:91]
	v_mfma_f32_16x16x32_bf16 v[80:83], v[194:197], v[218:221], v[80:83]
	v_mfma_f32_16x16x32_bf16 v[72:75], v[186:189], v[226:229], v[72:75]
	v_mfma_f32_16x16x32_bf16 v[64:67], v[194:197], v[226:229], v[64:67]
	v_mfma_f32_16x16x32_bf16 v[120:123], v[190:193], v[206:209], v[120:123]
	v_mfma_f32_16x16x32_bf16 v[112:115], v[198:201], v[206:209], v[112:115]
	v_mfma_f32_16x16x32_bf16 v[104:107], v[190:193], v[214:217], v[104:107]
	v_mfma_f32_16x16x32_bf16 v[96:99], v[198:201], v[214:217], v[96:99]
	v_mfma_f32_16x16x32_bf16 v[88:91], v[190:193], v[222:225], v[88:91]
	v_mfma_f32_16x16x32_bf16 v[80:83], v[198:201], v[222:225], v[80:83]
	v_mfma_f32_16x16x32_bf16 v[72:75], v[190:193], v[236:239], v[72:75]
	v_mfma_f32_16x16x32_bf16 v[64:67], v[198:201], v[236:239], v[64:67]
	s_barrier
	s_setprio 0
	s_add_i32 s51, s44, s3
	v_lshl_add_u64 v[150:151], s[26:27], 0, v[158:159]
	s_mov_b32 m0, s51
	ds_read_b128 v[202:205], v146 offset:16384
	ds_read_b128 v[206:209], v146 offset:17408
	ds_read_b128 v[210:213], v146 offset:18432
	ds_read_b128 v[214:217], v146 offset:19456
	ds_read_b128 v[218:221], v146 offset:20480
	ds_read_b128 v[222:225], v146 offset:21504
	ds_read_b128 v[226:229], v146 offset:22528
	ds_read_b128 v[236:239], v146 offset:23552
	global_load_lds_dwordx4 v[150:151], off
	s_add_i32 m0, s51, 0x2000
	s_add_u32 s52, s26, 0x40000
	v_lshl_add_u64 v[246:247], s[26:27], 0, v[162:163]
	s_addc_u32 s53, s27, 0
	s_add_i32 s51, s45, s3
	global_load_lds_dwordx4 v[246:247], off
	v_lshl_add_u64 v[248:249], s[52:53], 0, v[158:159]
	s_mov_b32 m0, s51
	v_lshl_add_u64 v[250:251], s[28:29], 0, v[160:161]
	global_load_lds_dwordx4 v[248:249], off
	v_lshl_add_u64 v[248:249], s[52:53], 0, v[162:163]
	s_add_i32 m0, s51, 0x2000
	s_nop 0
	global_load_lds_dwordx4 v[248:249], off
	v_lshl_add_u64 v[248:249], s[28:29], 0, v[156:157]
	s_mov_b32 m0, s33
	s_nop 0
	global_load_lds_dwordx4 v[248:249], off
	s_mov_b32 m0, s34
	s_nop 0
	global_load_lds_dwordx4 v[250:251], off
	s_waitcnt vmcnt(8)
	s_waitcnt lgkmcnt(0)
	s_setprio 1
	s_barrier
; #define PG8_STAGE(bufoff, gbase, voff) do { _Pragma("unroll") for (int _i = 0; _i < 2; ++_i) \
;         __builtin_amdgcn_global_load_lds((const unsigned*)((const char*)(gbase) + (voff)[_i]), (PG8_LAS unsigned*)(lds + (bufoff) + ldsw + _i * 8192), 16, 0, 0); } while (0)
; #define PG8_LDA(dst, b, h) do { _Pragma("unroll") for (int m = 0; m < 4; ++m) _Pragma("unroll") for (int k = 0; k < 2; ++k) dst[m][k] = *(const PG8_LAS bf16x8*)(lds + PG8_SA(b, h) + aoff + m * 2048 + k * 1024); } while (0)
; #define PG8_LDB(dst, b, h) do { _Pragma("unroll") for (int n = 0; n < 2; ++n) _Pragma("unroll") for (int k = 0; k < 2; ++k) dst[n][k] = *(const PG8_LAS bf16x8*)(lds + PG8_SB(b, h) + boff + n * 2048 + k * 1024); } while (0)
; #define PG8_MMA(ai, bj, At, Bt) do { __builtin_amdgcn_s_setprio(1); _Pragma("unroll") for (int m = 0; m < 4; ++m) _Pragma("unroll") for (int n = 0; n < 2; ++n) _Pragma("unroll") for (int k = 0; k < 2; ++k) \
;         acc[ai][bj][m][n] = __builtin_amdgcn_mfma_f32_16x16x32_bf16(Bt[n][k], At[m][k], acc[ai][bj][m][n], 0, 0, 0); __builtin_amdgcn_s_setprio(0); } while (0)
; #define PG8_WAIT_V(n) asm volatile("s_waitcnt vmcnt(" #n ")" ::: "memory")
; #define PG8_WAIT_L(n) asm volatile("s_waitcnt lgkmcnt(" #n ")" ::: "memory")
; #define PG8_BAR __builtin_amdgcn_s_barrier()
; #define PG8_SCHED __builtin_amdgcn_sched_barrier(0)
; template <class Epi, class Sched, bool ALIGN_EPI = false, bool SP2 = false>
; __device__ __forceinline__ void gemm_phase(PG8_LAS unsigned char* lds, const Gemm g, const Sched& S, const Epi& E) {
;     ...
;             PG8_WAIT_V(8); PG8_WAIT_L(0); PG8_BAR; PG8_MMA(1, 0, At, B0); PG8_MMA(1, 1, At, B1); PG8_BAR; PG8_SCHED;
;             PG8_LDB(B0, 1, 0); PG8_LDB(B1, 1, 1); PG8_SCHED; PG8_LDA(At, 1, 0); PG8_STAGE(PG8_SA(0, 1), a2 + hstep, voffA);
;             PG8_WAIT_V(8); PG8_WAIT_L(0); PG8_BAR; PG8_MMA(0, 0, At, B0); PG8_MMA(0, 1, At, B1); PG8_BAR; PG8_SCHED;
	v_mfma_f32_16x16x32_bf16 v[60:63], v[136:139], v[202:205], v[60:63]
	v_mfma_f32_16x16x32_bf16 v[52:55], v[178:181], v[202:205], v[52:55]
	v_mfma_f32_16x16x32_bf16 v[44:47], v[136:139], v[210:213], v[44:47]
	v_mfma_f32_16x16x32_bf16 v[36:39], v[178:181], v[210:213], v[36:39]
	v_mfma_f32_16x16x32_bf16 v[28:31], v[136:139], v[218:221], v[28:31]
	v_mfma_f32_16x16x32_bf16 v[20:23], v[178:181], v[218:221], v[20:23]
	v_mfma_f32_16x16x32_bf16 v[12:15], v[136:139], v[226:229], v[12:15]
	v_mfma_f32_16x16x32_bf16 v[4:7], v[178:181], v[226:229], v[4:7]
	v_mfma_f32_16x16x32_bf16 v[60:63], v[174:177], v[206:209], v[60:63]
	v_mfma_f32_16x16x32_bf16 v[52:55], v[182:185], v[206:209], v[52:55]
	v_mfma_f32_16x16x32_bf16 v[44:47], v[174:177], v[214:217], v[44:47]
	v_mfma_f32_16x16x32_bf16 v[36:39], v[182:185], v[214:217], v[36:39]
	v_mfma_f32_16x16x32_bf16 v[28:31], v[174:177], v[222:225], v[28:31]
	v_mfma_f32_16x16x32_bf16 v[20:23], v[182:185], v[222:225], v[20:23]
	v_mfma_f32_16x16x32_bf16 v[12:15], v[174:177], v[236:239], v[12:15]
	v_mfma_f32_16x16x32_bf16 v[4:7], v[182:185], v[236:239], v[4:7]
	s_setprio 0
	s_setprio 1
	v_mfma_f32_16x16x32_bf16 v[56:59], v[186:189], v[202:205], v[56:59]
	v_mfma_f32_16x16x32_bf16 v[48:51], v[194:197], v[202:205], v[48:51]
	v_mfma_f32_16x16x32_bf16 v[40:43], v[186:189], v[210:213], v[40:43]
	v_mfma_f32_16x16x32_bf16 v[32:35], v[194:197], v[210:213], v[32:35]
	v_mfma_f32_16x16x32_bf16 v[24:27], v[186:189], v[218:221], v[24:27]
	v_mfma_f32_16x16x32_bf16 v[16:19], v[194:197], v[218:221], v[16:19]
	v_mfma_f32_16x16x32_bf16 v[8:11], v[186:189], v[226:229], v[8:11]
	v_mfma_f32_16x16x32_bf16 v[0:3], v[194:197], v[226:229], v[0:3]
	v_mfma_f32_16x16x32_bf16 v[56:59], v[190:193], v[206:209], v[56:59]
	v_mfma_f32_16x16x32_bf16 v[48:51], v[198:201], v[206:209], v[48:51]
	v_mfma_f32_16x16x32_bf16 v[40:43], v[190:193], v[214:217], v[40:43]
	v_mfma_f32_16x16x32_bf16 v[32:35], v[198:201], v[214:217], v[32:35]
	v_mfma_f32_16x16x32_bf16 v[24:27], v[190:193], v[222:225], v[24:27]
	v_mfma_f32_16x16x32_bf16 v[16:19], v[198:201], v[222:225], v[16:19]
	v_mfma_f32_16x16x32_bf16 v[8:11], v[190:193], v[236:239], v[8:11]
	v_mfma_f32_16x16x32_bf16 v[0:3], v[198:201], v[236:239], v[0:3]
	s_barrier
	s_setprio 0
	s_add_i32 s51, 0, 0x18000
	v_add_u32_e32 v149, s51, v141
	s_add_i32 s52, 0, 0x1c000
	ds_read_b128 v[136:139], v149
	ds_read_b128 v[174:177], v149 offset:1024
	ds_read_b128 v[178:181], v149 offset:2048
	ds_read_b128 v[182:185], v149 offset:3072
	v_add_u32_e32 v149, s52, v141
	ds_read_b128 v[186:189], v149
	ds_read_b128 v[190:193], v149 offset:1024
	ds_read_b128 v[194:197], v149 offset:2048
	ds_read_b128 v[198:201], v149 offset:3072
	s_add_u32 s28, s28, 0x40000
	s_addc_u32 s29, s29, 0
	s_mov_b32 m0, s35
	v_lshl_add_u64 v[252:253], s[28:29], 0, v[156:157]
	ds_read_b128 v[202:205], v146 offset:32768
	ds_read_b128 v[206:209], v146 offset:33792
	ds_read_b128 v[210:213], v146 offset:34816
	ds_read_b128 v[214:217], v146 offset:35840
	ds_read_b128 v[218:221], v146 offset:36864
	ds_read_b128 v[222:225], v146 offset:37888
	ds_read_b128 v[226:229], v146 offset:38912
	ds_read_b128 v[236:239], v146 offset:39936
	global_load_lds_dwordx4 v[252:253], off
	v_lshl_add_u64 v[252:253], s[28:29], 0, v[160:161]
	s_mov_b32 m0, s36
	s_nop 0
	global_load_lds_dwordx4 v[252:253], off
	s_waitcnt vmcnt(8)
	s_waitcnt lgkmcnt(0)
	s_setprio 1
	s_barrier
	v_mfma_f32_16x16x32_bf16 v[124:127], v[136:139], v[202:205], v[124:127]
	v_mfma_f32_16x16x32_bf16 v[116:119], v[178:181], v[202:205], v[116:119]
	v_mfma_f32_16x16x32_bf16 v[108:111], v[136:139], v[210:213], v[108:111]
	v_mfma_f32_16x16x32_bf16 v[100:103], v[178:181], v[210:213], v[100:103]
	v_mfma_f32_16x16x32_bf16 v[92:95], v[136:139], v[218:221], v[92:95]
	v_mfma_f32_16x16x32_bf16 v[84:87], v[178:181], v[218:221], v[84:87]
	v_mfma_f32_16x16x32_bf16 v[76:79], v[136:139], v[226:229], v[76:79]
	v_mfma_f32_16x16x32_bf16 v[68:71], v[178:181], v[226:229], v[68:71]
	v_mfma_f32_16x16x32_bf16 v[124:127], v[174:177], v[206:209], v[124:127]
	v_mfma_f32_16x16x32_bf16 v[116:119], v[182:185], v[206:209], v[116:119]
	v_mfma_f32_16x16x32_bf16 v[108:111], v[174:177], v[214:217], v[108:111]
	v_mfma_f32_16x16x32_bf16 v[100:103], v[182:185], v[214:217], v[100:103]
	v_mfma_f32_16x16x32_bf16 v[92:95], v[174:177], v[222:225], v[92:95]
	v_mfma_f32_16x16x32_bf16 v[84:87], v[182:185], v[222:225], v[84:87]
	v_mfma_f32_16x16x32_bf16 v[76:79], v[174:177], v[236:239], v[76:79]
	v_mfma_f32_16x16x32_bf16 v[68:71], v[182:185], v[236:239], v[68:71]
	s_setprio 0
	s_setprio 1
	v_mfma_f32_16x16x32_bf16 v[120:123], v[186:189], v[202:205], v[120:123]
	v_mfma_f32_16x16x32_bf16 v[112:115], v[194:197], v[202:205], v[112:115]
	v_mfma_f32_16x16x32_bf16 v[104:107], v[186:189], v[210:213], v[104:107]
	v_mfma_f32_16x16x32_bf16 v[96:99], v[194:197], v[210:213], v[96:99]
	v_mfma_f32_16x16x32_bf16 v[88:91], v[186:189], v[218:221], v[88:91]
	v_mfma_f32_16x16x32_bf16 v[80:83], v[194:197], v[218:221], v[80:83]
	v_mfma_f32_16x16x32_bf16 v[72:75], v[186:189], v[226:229], v[72:75]
	v_mfma_f32_16x16x32_bf16 v[64:67], v[194:197], v[226:229], v[64:67]
	v_mfma_f32_16x16x32_bf16 v[120:123], v[190:193], v[206:209], v[120:123]
	v_mfma_f32_16x16x32_bf16 v[112:115], v[198:201], v[206:209], v[112:115]
	v_mfma_f32_16x16x32_bf16 v[104:107], v[190:193], v[214:217], v[104:107]
	v_mfma_f32_16x16x32_bf16 v[96:99], v[198:201], v[214:217], v[96:99]
	v_mfma_f32_16x16x32_bf16 v[88:91], v[190:193], v[222:225], v[88:91]
	v_mfma_f32_16x16x32_bf16 v[80:83], v[198:201], v[222:225], v[80:83]
	v_mfma_f32_16x16x32_bf16 v[72:75], v[190:193], v[236:239], v[72:75]
	v_mfma_f32_16x16x32_bf16 v[64:67], v[198:201], v[236:239], v[64:67]
	s_barrier
; #define PG8_STAGE(bufoff, gbase, voff) do { _Pragma("unroll") for (int _i = 0; _i < 2; ++_i) \
;         __builtin_amdgcn_global_load_lds((const unsigned*)((const char*)(gbase) + (voff)[_i]), (PG8_LAS unsigned*)(lds + (bufoff) + ldsw + _i * 8192), 16, 0, 0); } while (0)
; #define PG8_LDA(dst, b, h) do { _Pragma("unroll") for (int m = 0; m < 4; ++m) _Pragma("unroll") for (int k = 0; k < 2; ++k) dst[m][k] = *(const PG8_LAS bf16x8*)(lds + PG8_SA(b, h) + aoff + m * 2048 + k * 1024); } while (0)
; #define PG8_MMA(ai, bj, At, Bt) do { __builtin_amdgcn_s_setprio(1); _Pragma("unroll") for (int m = 0; m < 4; ++m) _Pragma("unroll") for (int n = 0; n < 2; ++n) _Pragma("unroll") for (int k = 0; k < 2; ++k) \
;         acc[ai][bj][m][n] = __builtin_amdgcn_mfma_f32_16x16x32_bf16(Bt[n][k], At[m][k], acc[ai][bj][m][n], 0, 0, 0); __builtin_amdgcn_s_setprio(0); } while (0)
; #define PG8_WAIT_V(n) asm volatile("s_waitcnt vmcnt(" #n ")" ::: "memory")
; #define PG8_WAIT_L(n) asm volatile("s_waitcnt lgkmcnt(" #n ")" ::: "memory")
; #define PG8_BAR __builtin_amdgcn_s_barrier()
; #define PG8_SCHED __builtin_amdgcn_sched_barrier(0)
; template <class Epi, class Sched, bool ALIGN_EPI = false, bool SP2 = false>
; __device__ __forceinline__ void gemm_phase(PG8_LAS unsigned char* lds, const Gemm g, const Sched& S, const Epi& E) {
;     ...
;             PG8_LDA(At, 1, 1); PG8_STAGE(PG8_SB(1, 0), b3, voffB); PG8_STAGE(PG8_SB(1, 1), b3 + hstep, voffB); PG8_STAGE(PG8_SA(1, 0), a3, voffA);
;             PG8_WAIT_V(8); PG8_WAIT_L(0); PG8_BAR; PG8_MMA(1, 0, At, B0); PG8_MMA(1, 1, At, B1); PG8_BAR; PG8_SCHED;
;     ...
;         if constexpr (ALIGN_EPI) { if (wr == 0) PG8_BAR; }
	s_setprio 0
	s_add_i32 s28, s51, s3
	v_lshl_add_u64 v[150:151], v[150:151], 0, s[6:7]
	s_mov_b32 m0, s28
	ds_read_b128 v[202:205], v146 offset:49152
	ds_read_b128 v[206:209], v146 offset:50176
	ds_read_b128 v[210:213], v146 offset:51200
	ds_read_b128 v[214:217], v146 offset:52224
	ds_read_b128 v[218:221], v146 offset:53248
	ds_read_b128 v[222:225], v146 offset:54272
	ds_read_b128 v[226:229], v146 offset:55296
	ds_read_b128 v[236:239], v146 offset:56320
	global_load_lds_dwordx4 v[150:151], off
	s_add_i32 m0, s28, 0x2000
	s_add_u32 s26, s26, 0x40080
	v_lshl_add_u64 v[150:151], v[246:247], 0, s[6:7]
	s_addc_u32 s27, s27, 0
	s_add_i32 s28, s52, s3
	global_load_lds_dwordx4 v[150:151], off
	v_lshl_add_u64 v[150:151], s[26:27], 0, v[158:159]
	s_mov_b32 m0, s28
	s_nop 0
	global_load_lds_dwordx4 v[150:151], off
	v_lshl_add_u64 v[150:151], s[26:27], 0, v[162:163]
	s_add_i32 m0, s28, 0x2000
	s_nop 0
	global_load_lds_dwordx4 v[150:151], off
	v_lshl_add_u64 v[150:151], v[248:249], 0, s[6:7]
	s_mov_b32 m0, s38
	s_nop 0
	global_load_lds_dwordx4 v[150:151], off
	v_lshl_add_u64 v[150:151], v[250:251], 0, s[6:7]
	s_mov_b32 m0, s39
	s_nop 0
	global_load_lds_dwordx4 v[150:151], off
	s_waitcnt vmcnt(8)
	s_waitcnt lgkmcnt(0)
	s_setprio 1
	s_barrier
	v_mfma_f32_16x16x32_bf16 v[60:63], v[136:139], v[202:205], v[60:63]
	v_mfma_f32_16x16x32_bf16 v[52:55], v[178:181], v[202:205], v[52:55]
	v_mfma_f32_16x16x32_bf16 v[44:47], v[136:139], v[210:213], v[44:47]
	v_mfma_f32_16x16x32_bf16 v[36:39], v[178:181], v[210:213], v[36:39]
	v_mfma_f32_16x16x32_bf16 v[28:31], v[136:139], v[218:221], v[28:31]
	v_mfma_f32_16x16x32_bf16 v[20:23], v[178:181], v[218:221], v[20:23]
	v_mfma_f32_16x16x32_bf16 v[12:15], v[136:139], v[226:229], v[12:15]
	v_mfma_f32_16x16x32_bf16 v[4:7], v[178:181], v[226:229], v[4:7]
	v_mfma_f32_16x16x32_bf16 v[60:63], v[174:177], v[206:209], v[60:63]
	v_mfma_f32_16x16x32_bf16 v[52:55], v[182:185], v[206:209], v[52:55]
	v_mfma_f32_16x16x32_bf16 v[44:47], v[174:177], v[214:217], v[44:47]
	v_mfma_f32_16x16x32_bf16 v[36:39], v[182:185], v[214:217], v[36:39]
	v_mfma_f32_16x16x32_bf16 v[28:31], v[174:177], v[222:225], v[28:31]
	v_mfma_f32_16x16x32_bf16 v[20:23], v[182:185], v[222:225], v[20:23]
	v_mfma_f32_16x16x32_bf16 v[12:15], v[174:177], v[236:239], v[12:15]
	v_mfma_f32_16x16x32_bf16 v[4:7], v[182:185], v[236:239], v[4:7]
	s_setprio 0
	s_setprio 1
	v_mfma_f32_16x16x32_bf16 v[56:59], v[186:189], v[202:205], v[56:59]
	v_mfma_f32_16x16x32_bf16 v[48:51], v[194:197], v[202:205], v[48:51]
	v_mfma_f32_16x16x32_bf16 v[40:43], v[186:189], v[210:213], v[40:43]
	v_mfma_f32_16x16x32_bf16 v[32:35], v[194:197], v[210:213], v[32:35]
	v_mfma_f32_16x16x32_bf16 v[24:27], v[186:189], v[218:221], v[24:27]
	v_mfma_f32_16x16x32_bf16 v[16:19], v[194:197], v[218:221], v[16:19]
	v_mfma_f32_16x16x32_bf16 v[8:11], v[186:189], v[226:229], v[8:11]
	v_mfma_f32_16x16x32_bf16 v[0:3], v[194:197], v[226:229], v[0:3]
	v_mfma_f32_16x16x32_bf16 v[56:59], v[190:193], v[206:209], v[56:59]
	v_mfma_f32_16x16x32_bf16 v[48:51], v[198:201], v[206:209], v[48:51]
	v_mfma_f32_16x16x32_bf16 v[40:43], v[190:193], v[214:217], v[40:43]
	v_mfma_f32_16x16x32_bf16 v[32:35], v[198:201], v[214:217], v[32:35]
	v_mfma_f32_16x16x32_bf16 v[24:27], v[190:193], v[222:225], v[24:27]
	v_mfma_f32_16x16x32_bf16 v[16:19], v[198:201], v[222:225], v[16:19]
	v_mfma_f32_16x16x32_bf16 v[8:11], v[190:193], v[236:239], v[8:11]
	v_mfma_f32_16x16x32_bf16 v[0:3], v[198:201], v[236:239], v[0:3]
	s_barrier
	s_setprio 0
	s_add_i32 s50, s50, 2
	s_add_u32 s24, s24, 0x100
	s_addc_u32 s25, s25, 0
	s_add_u32 s48, s48, 0x100
	s_addc_u32 s49, s49, 0
	s_cmp_gt_u32 s50, 13
	s_cbranch_scc0 .LBB0_1322
	s_and_b64 vcc, exec, s[14:15]
	s_cbranch_vccz .LBB0_1325
	s_barrier

; #define PG8_STAGE(bufoff, gbase, voff) do { _Pragma("unroll") for (int _i = 0; _i < 2; ++_i) \
;         __builtin_amdgcn_global_load_lds((const unsigned*)((const char*)(gbase) + (voff)[_i]), (PG8_LAS unsigned*)(lds + (bufoff) + ldsw + _i * 8192), 16, 0, 0); } while (0)
; #define PG8_LDA(dst, b, h) do { _Pragma("unroll") for (int m = 0; m < 4; ++m) _Pragma("unroll") for (int k = 0; k < 2; ++k) dst[m][k] = *(const PG8_LAS bf16x8*)(lds + PG8_SA(b, h) + aoff + m * 2048 + k * 1024); } while (0)
; #define PG8_LDB(dst, b, h) do { _Pragma("unroll") for (int n = 0; n < 2; ++n) _Pragma("unroll") for (int k = 0; k < 2; ++k) dst[n][k] = *(const PG8_LAS bf16x8*)(lds + PG8_SB(b, h) + boff + n * 2048 + k * 1024); } while (0)
; #define PG8_MMA(ai, bj, At, Bt) do { __builtin_amdgcn_s_setprio(1); _Pragma("unroll") for (int m = 0; m < 4; ++m) _Pragma("unroll") for (int n = 0; n < 2; ++n) _Pragma("unroll") for (int k = 0; k < 2; ++k) \
;         acc[ai][bj][m][n] = __builtin_amdgcn_mfma_f32_16x16x32_bf16(Bt[n][k], At[m][k], acc[ai][bj][m][n], 0, 0, 0); __builtin_amdgcn_s_setprio(0); } while (0)
; #define PG8_WAIT_V(n) asm volatile("s_waitcnt vmcnt(" #n ")" ::: "memory")
; #define PG8_WAIT_L(n) asm volatile("s_waitcnt lgkmcnt(" #n ")" ::: "memory")
; template <class Epi, class Sched, bool ALIGN_EPI = false, bool SP2 = false>
; __device__ __forceinline__ void gemm_phase(PG8_LAS unsigned char* lds, const Gemm g, const Sched& S, const Epi& E) {
;     ...
;             const bool last = (t == nt - 2);
;             const char* a1 = cA + (size_t)(t + 1) * kstep;
;             const char* a2 = last ? nA : cA + (size_t)(t + 2) * kstep; const char* b2 = last ? nB : cB + (size_t)(t + 2) * kstep;
;             const char* a3 = a2 + kstep; const char* b3 = b2 + kstep;
;             if (last && has_next) S.a_ready(nxt);
;             if constexpr (SP2) {
;             PG8_LDB(B0, 0, 0); PG8_LDB(B1, 0, 1); PG8_SCHED; PG8_LDA(At, 0, 0); PG8_STAGE(PG8_SA(1, 1), a1 + hstep, voffA);
;             PG8_WAIT_V(8); PG8_WAIT_L(0); PG8_BAR; PG8_MMA(0, 0, At, B0); PG8_MMA(0, 1, At, B1); PG8_BAR; PG8_SCHED;
;             PG8_LDA(At, 0, 1); PG8_STAGE(PG8_SB(0, 0), b2, voffB); PG8_STAGE(PG8_SB(0, 1), b2 + hstep, voffB); PG8_STAGE(PG8_SA(0, 0), a2, voffA);
;             PG8_WAIT_V(8); PG8_WAIT_L(0); PG8_BAR; PG8_MMA(1, 0, At, B0); PG8_MMA(1, 1, At, B1); PG8_BAR; PG8_SCHED;
.LBB0_1442:
	ds_read_b128 v[128:131], v213
	ds_read_b128 v[132:135], v213 offset:1024
	ds_read_b128 v[136:139], v213 offset:2048
	ds_read_b128 v[140:143], v213 offset:3072
	ds_read_b128 v[144:147], v214
	ds_read_b128 v[148:151], v214 offset:1024
	ds_read_b128 v[172:175], v214 offset:2048
	ds_read_b128 v[176:179], v214 offset:3072
	s_add_u32 s10, s6, 0xfff50080
	s_addc_u32 s11, s7, -1
	s_cmp_eq_u32 s50, 40
	s_cselect_b32 s27, s23, s11
	s_cselect_b32 s26, s22, s10
	s_cselect_b32 s11, s25, s49
	s_cselect_b32 s10, s24, s48
	v_lshl_add_u64 v[162:163], s[6:7], 0, v[154:155]
	s_add_i32 m0, s29, 0xc000
	ds_read_b128 v[180:183], v215
	ds_read_b128 v[184:187], v215 offset:1024
	ds_read_b128 v[188:191], v215 offset:2048
	ds_read_b128 v[192:195], v215 offset:3072
	ds_read_b128 v[196:199], v215 offset:4096
	ds_read_b128 v[200:203], v215 offset:5120
	ds_read_b128 v[204:207], v215 offset:6144
	ds_read_b128 v[220:223], v215 offset:7168
	global_load_lds_dwordx4 v[162:163], off
	v_lshl_add_u64 v[162:163], s[6:7], 0, v[156:157]
	s_add_i32 m0, s29, 0xe000
	s_nop 0
	global_load_lds_dwordx4 v[162:163], off
	s_waitcnt vmcnt(8)
	s_waitcnt lgkmcnt(0)
	s_setprio 1
	s_barrier
	v_mfma_f32_16x16x32_bf16 v[124:127], v[128:131], v[180:183], v[124:127]
	v_mfma_f32_16x16x32_bf16 v[120:123], v[136:139], v[180:183], v[120:123]
	v_mfma_f32_16x16x32_bf16 v[108:111], v[128:131], v[188:191], v[108:111]
	v_mfma_f32_16x16x32_bf16 v[104:107], v[136:139], v[188:191], v[104:107]
	v_mfma_f32_16x16x32_bf16 v[92:95], v[128:131], v[196:199], v[92:95]
	v_mfma_f32_16x16x32_bf16 v[88:91], v[136:139], v[196:199], v[88:91]
	v_mfma_f32_16x16x32_bf16 v[76:79], v[128:131], v[204:207], v[76:79]
	v_mfma_f32_16x16x32_bf16 v[72:75], v[136:139], v[204:207], v[72:75]
	v_mfma_f32_16x16x32_bf16 v[124:127], v[132:135], v[184:187], v[124:127]
	v_mfma_f32_16x16x32_bf16 v[120:123], v[140:143], v[184:187], v[120:123]
	v_mfma_f32_16x16x32_bf16 v[108:111], v[132:135], v[192:195], v[108:111]
	v_mfma_f32_16x16x32_bf16 v[104:107], v[140:143], v[192:195], v[104:107]
	v_mfma_f32_16x16x32_bf16 v[92:95], v[132:135], v[200:203], v[92:95]
	v_mfma_f32_16x16x32_bf16 v[88:91], v[140:143], v[200:203], v[88:91]
	v_mfma_f32_16x16x32_bf16 v[76:79], v[132:135], v[220:223], v[76:79]
	v_mfma_f32_16x16x32_bf16 v[72:75], v[140:143], v[220:223], v[72:75]
	s_setprio 0
	s_setprio 1
	v_mfma_f32_16x16x32_bf16 v[116:119], v[144:147], v[180:183], v[116:119]
	v_mfma_f32_16x16x32_bf16 v[112:115], v[172:175], v[180:183], v[112:115]
	v_mfma_f32_16x16x32_bf16 v[100:103], v[144:147], v[188:191], v[100:103]
	v_mfma_f32_16x16x32_bf16 v[96:99], v[172:175], v[188:191], v[96:99]
	v_mfma_f32_16x16x32_bf16 v[84:87], v[144:147], v[196:199], v[84:87]
	v_mfma_f32_16x16x32_bf16 v[80:83], v[172:175], v[196:199], v[80:83]
	v_mfma_f32_16x16x32_bf16 v[68:71], v[144:147], v[204:207], v[68:71]
	v_mfma_f32_16x16x32_bf16 v[64:67], v[172:175], v[204:207], v[64:67]
	v_mfma_f32_16x16x32_bf16 v[116:119], v[148:151], v[184:187], v[116:119]
	v_mfma_f32_16x16x32_bf16 v[112:115], v[176:179], v[184:187], v[112:115]
	v_mfma_f32_16x16x32_bf16 v[100:103], v[148:151], v[192:195], v[100:103]
	v_mfma_f32_16x16x32_bf16 v[96:99], v[176:179], v[192:195], v[96:99]
	v_mfma_f32_16x16x32_bf16 v[84:87], v[148:151], v[200:203], v[84:87]
	v_mfma_f32_16x16x32_bf16 v[80:83], v[176:179], v[200:203], v[80:83]
	v_mfma_f32_16x16x32_bf16 v[68:71], v[148:151], v[220:223], v[68:71]
	v_mfma_f32_16x16x32_bf16 v[64:67], v[176:179], v[220:223], v[64:67]
	s_barrier
	s_setprio 0
	s_add_i32 s51, s41, s28
	v_lshl_add_u64 v[162:163], s[10:11], 0, v[166:167]
	s_mov_b32 m0, s51
	ds_read_b128 v[180:183], v215 offset:16384
	ds_read_b128 v[184:187], v215 offset:17408
	ds_read_b128 v[188:191], v215 offset:18432
	ds_read_b128 v[192:195], v215 offset:19456
	ds_read_b128 v[196:199], v215 offset:20480
	ds_read_b128 v[200:203], v215 offset:21504
	ds_read_b128 v[204:207], v215 offset:22528
	ds_read_b128 v[220:223], v215 offset:23552
	global_load_lds_dwordx4 v[162:163], off
	s_add_i32 m0, s51, 0x2000
	s_add_u32 s52, s10, 0xb0000
	v_lshl_add_u64 v[208:209], s[10:11], 0, v[170:171]
	s_addc_u32 s53, s11, 0
	s_add_i32 s51, s42, s28
	global_load_lds_dwordx4 v[208:209], off
	v_lshl_add_u64 v[224:225], s[52:53], 0, v[166:167]
	s_mov_b32 m0, s51
	v_lshl_add_u64 v[226:227], s[26:27], 0, v[168:169]
	global_load_lds_dwordx4 v[224:225], off
	v_lshl_add_u64 v[224:225], s[52:53], 0, v[170:171]
	s_add_i32 m0, s51, 0x2000
	s_nop 0
	global_load_lds_dwordx4 v[224:225], off
	v_lshl_add_u64 v[224:225], s[26:27], 0, v[164:165]
	s_mov_b32 m0, s29
	s_nop 0
	global_load_lds_dwordx4 v[224:225], off
	s_mov_b32 m0, s30
	s_nop 0
	global_load_lds_dwordx4 v[226:227], off
	s_waitcnt vmcnt(8)
	s_waitcnt lgkmcnt(0)
	s_setprio 1
	s_barrier
; #define PG8_STAGE(bufoff, gbase, voff) do { _Pragma("unroll") for (int _i = 0; _i < 2; ++_i) \
;         __builtin_amdgcn_global_load_lds((const unsigned*)((const char*)(gbase) + (voff)[_i]), (PG8_LAS unsigned*)(lds + (bufoff) + ldsw + _i * 8192), 16, 0, 0); } while (0)
; #define PG8_LDA(dst, b, h) do { _Pragma("unroll") for (int m = 0; m < 4; ++m) _Pragma("unroll") for (int k = 0; k < 2; ++k) dst[m][k] = *(const PG8_LAS bf16x8*)(lds + PG8_SA(b, h) + aoff + m * 2048 + k * 1024); } while (0)
; #define PG8_LDB(dst, b, h) do { _Pragma("unroll") for (int n = 0; n < 2; ++n) _Pragma("unroll") for (int k = 0; k < 2; ++k) dst[n][k] = *(const PG8_LAS bf16x8*)(lds + PG8_SB(b, h) + boff + n * 2048 + k * 1024); } while (0)
; #define PG8_MMA(ai, bj, At, Bt) do { __builtin_amdgcn_s_setprio(1); _Pragma("unroll") for (int m = 0; m < 4; ++m) _Pragma("unroll") for (int n = 0; n < 2; ++n) _Pragma("unroll") for (int k = 0; k < 2; ++k) \
;         acc[ai][bj][m][n] = __builtin_amdgcn_mfma_f32_16x16x32_bf16(Bt[n][k], At[m][k], acc[ai][bj][m][n], 0, 0, 0); __builtin_amdgcn_s_setprio(0); } while (0)
; #define PG8_WAIT_V(n) asm volatile("s_waitcnt vmcnt(" #n ")" ::: "memory")
; #define PG8_WAIT_L(n) asm volatile("s_waitcnt lgkmcnt(" #n ")" ::: "memory")
; #define PG8_BAR __builtin_amdgcn_s_barrier()
; #define PG8_SCHED __builtin_amdgcn_sched_barrier(0)
; template <class Epi, class Sched, bool ALIGN_EPI = false, bool SP2 = false>
; __device__ __forceinline__ void gemm_phase(PG8_LAS unsigned char* lds, const Gemm g, const Sched& S, const Epi& E) {
;     ...
;             PG8_WAIT_V(8); PG8_WAIT_L(0); PG8_BAR; PG8_MMA(1, 0, At, B0); PG8_MMA(1, 1, At, B1); PG8_BAR; PG8_SCHED;
;             PG8_LDB(B0, 1, 0); PG8_LDB(B1, 1, 1); PG8_SCHED; PG8_LDA(At, 1, 0); PG8_STAGE(PG8_SA(0, 1), a2 + hstep, voffA);
;             PG8_WAIT_V(8); PG8_WAIT_L(0); PG8_BAR; PG8_MMA(0, 0, At, B0); PG8_MMA(0, 1, At, B1); PG8_BAR; PG8_SCHED;
	v_mfma_f32_16x16x32_bf16 v[60:63], v[128:131], v[180:183], v[60:63]
	v_mfma_f32_16x16x32_bf16 v[56:59], v[136:139], v[180:183], v[56:59]
	v_mfma_f32_16x16x32_bf16 v[44:47], v[128:131], v[188:191], v[44:47]
	v_mfma_f32_16x16x32_bf16 v[40:43], v[136:139], v[188:191], v[40:43]
	v_mfma_f32_16x16x32_bf16 v[28:31], v[128:131], v[196:199], v[28:31]
	v_mfma_f32_16x16x32_bf16 v[24:27], v[136:139], v[196:199], v[24:27]
	v_mfma_f32_16x16x32_bf16 v[12:15], v[128:131], v[204:207], v[12:15]
	v_mfma_f32_16x16x32_bf16 v[8:11], v[136:139], v[204:207], v[8:11]
	v_mfma_f32_16x16x32_bf16 v[60:63], v[132:135], v[184:187], v[60:63]
	v_mfma_f32_16x16x32_bf16 v[56:59], v[140:143], v[184:187], v[56:59]
	v_mfma_f32_16x16x32_bf16 v[44:47], v[132:135], v[192:195], v[44:47]
	v_mfma_f32_16x16x32_bf16 v[40:43], v[140:143], v[192:195], v[40:43]
	v_mfma_f32_16x16x32_bf16 v[28:31], v[132:135], v[200:203], v[28:31]
	v_mfma_f32_16x16x32_bf16 v[24:27], v[140:143], v[200:203], v[24:27]
	v_mfma_f32_16x16x32_bf16 v[12:15], v[132:135], v[220:223], v[12:15]
	v_mfma_f32_16x16x32_bf16 v[8:11], v[140:143], v[220:223], v[8:11]
	s_setprio 0
	s_setprio 1
	v_mfma_f32_16x16x32_bf16 v[52:55], v[144:147], v[180:183], v[52:55]
	v_mfma_f32_16x16x32_bf16 v[48:51], v[172:175], v[180:183], v[48:51]
	v_mfma_f32_16x16x32_bf16 v[36:39], v[144:147], v[188:191], v[36:39]
	v_mfma_f32_16x16x32_bf16 v[32:35], v[172:175], v[188:191], v[32:35]
	v_mfma_f32_16x16x32_bf16 v[20:23], v[144:147], v[196:199], v[20:23]
	v_mfma_f32_16x16x32_bf16 v[16:19], v[172:175], v[196:199], v[16:19]
	v_mfma_f32_16x16x32_bf16 v[4:7], v[144:147], v[204:207], v[4:7]
	v_mfma_f32_16x16x32_bf16 v[0:3], v[172:175], v[204:207], v[0:3]
	v_mfma_f32_16x16x32_bf16 v[52:55], v[148:151], v[184:187], v[52:55]
	v_mfma_f32_16x16x32_bf16 v[48:51], v[176:179], v[184:187], v[48:51]
	v_mfma_f32_16x16x32_bf16 v[36:39], v[148:151], v[192:195], v[36:39]
	v_mfma_f32_16x16x32_bf16 v[32:35], v[176:179], v[192:195], v[32:35]
	v_mfma_f32_16x16x32_bf16 v[20:23], v[148:151], v[200:203], v[20:23]
	v_mfma_f32_16x16x32_bf16 v[16:19], v[176:179], v[200:203], v[16:19]
	v_mfma_f32_16x16x32_bf16 v[4:7], v[148:151], v[220:223], v[4:7]
	v_mfma_f32_16x16x32_bf16 v[0:3], v[176:179], v[220:223], v[0:3]
	s_barrier
	s_setprio 0
	s_add_i32 s51, 0, 0x18000
	s_add_i32 s52, 0, 0x1c000
	v_add_u32_e32 v140, s51, v211
	v_add_u32_e32 v176, s52, v211
	ds_read_b128 v[128:131], v140
	ds_read_b128 v[132:135], v140 offset:1024
	ds_read_b128 v[136:139], v140 offset:2048
	ds_read_b128 v[140:143], v140 offset:3072
	ds_read_b128 v[144:147], v176
	ds_read_b128 v[148:151], v176 offset:1024
	ds_read_b128 v[172:175], v176 offset:2048
	ds_read_b128 v[176:179], v176 offset:3072
	s_add_u32 s26, s26, 0xb0000
	s_addc_u32 s27, s27, 0
	s_mov_b32 m0, s31
	v_lshl_add_u64 v[228:229], s[26:27], 0, v[164:165]
	ds_read_b128 v[180:183], v215 offset:32768
	ds_read_b128 v[184:187], v215 offset:33792
	ds_read_b128 v[188:191], v215 offset:34816
	ds_read_b128 v[192:195], v215 offset:35840
	ds_read_b128 v[196:199], v215 offset:36864
	ds_read_b128 v[200:203], v215 offset:37888
	ds_read_b128 v[204:207], v215 offset:38912
	ds_read_b128 v[220:223], v215 offset:39936
	global_load_lds_dwordx4 v[228:229], off
	v_lshl_add_u64 v[228:229], s[26:27], 0, v[168:169]
	s_mov_b32 m0, s33
	s_nop 0
	global_load_lds_dwordx4 v[228:229], off
	s_waitcnt vmcnt(8)
	s_waitcnt lgkmcnt(0)
	s_setprio 1
	s_barrier
	v_mfma_f32_16x16x32_bf16 v[124:127], v[128:131], v[180:183], v[124:127]
	v_mfma_f32_16x16x32_bf16 v[120:123], v[136:139], v[180:183], v[120:123]
	v_mfma_f32_16x16x32_bf16 v[108:111], v[128:131], v[188:191], v[108:111]
	v_mfma_f32_16x16x32_bf16 v[104:107], v[136:139], v[188:191], v[104:107]
	v_mfma_f32_16x16x32_bf16 v[92:95], v[128:131], v[196:199], v[92:95]
	v_mfma_f32_16x16x32_bf16 v[88:91], v[136:139], v[196:199], v[88:91]
	v_mfma_f32_16x16x32_bf16 v[76:79], v[128:131], v[204:207], v[76:79]
	v_mfma_f32_16x16x32_bf16 v[72:75], v[136:139], v[204:207], v[72:75]
	v_mfma_f32_16x16x32_bf16 v[124:127], v[132:135], v[184:187], v[124:127]
	v_mfma_f32_16x16x32_bf16 v[120:123], v[140:143], v[184:187], v[120:123]
	v_mfma_f32_16x16x32_bf16 v[108:111], v[132:135], v[192:195], v[108:111]
	v_mfma_f32_16x16x32_bf16 v[104:107], v[140:143], v[192:195], v[104:107]
	v_mfma_f32_16x16x32_bf16 v[92:95], v[132:135], v[200:203], v[92:95]
	v_mfma_f32_16x16x32_bf16 v[88:91], v[140:143], v[200:203], v[88:91]
	v_mfma_f32_16x16x32_bf16 v[76:79], v[132:135], v[220:223], v[76:79]
	v_mfma_f32_16x16x32_bf16 v[72:75], v[140:143], v[220:223], v[72:75]
	s_setprio 0
	s_setprio 1
	v_mfma_f32_16x16x32_bf16 v[116:119], v[144:147], v[180:183], v[116:119]
	v_mfma_f32_16x16x32_bf16 v[112:115], v[172:175], v[180:183], v[112:115]
	v_mfma_f32_16x16x32_bf16 v[100:103], v[144:147], v[188:191], v[100:103]
	v_mfma_f32_16x16x32_bf16 v[96:99], v[172:175], v[188:191], v[96:99]
	v_mfma_f32_16x16x32_bf16 v[84:87], v[144:147], v[196:199], v[84:87]
	v_mfma_f32_16x16x32_bf16 v[80:83], v[172:175], v[196:199], v[80:83]
	v_mfma_f32_16x16x32_bf16 v[68:71], v[144:147], v[204:207], v[68:71]
	v_mfma_f32_16x16x32_bf16 v[64:67], v[172:175], v[204:207], v[64:67]
	v_mfma_f32_16x16x32_bf16 v[116:119], v[148:151], v[184:187], v[116:119]
	v_mfma_f32_16x16x32_bf16 v[112:115], v[176:179], v[184:187], v[112:115]
	v_mfma_f32_16x16x32_bf16 v[100:103], v[148:151], v[192:195], v[100:103]
	v_mfma_f32_16x16x32_bf16 v[96:99], v[176:179], v[192:195], v[96:99]
	v_mfma_f32_16x16x32_bf16 v[84:87], v[148:151], v[200:203], v[84:87]
	v_mfma_f32_16x16x32_bf16 v[80:83], v[176:179], v[200:203], v[80:83]
	v_mfma_f32_16x16x32_bf16 v[68:71], v[148:151], v[220:223], v[68:71]
	v_mfma_f32_16x16x32_bf16 v[64:67], v[176:179], v[220:223], v[64:67]
	s_barrier
; #define PG8_STAGE(bufoff, gbase, voff) do { _Pragma("unroll") for (int _i = 0; _i < 2; ++_i) \
;         __builtin_amdgcn_global_load_lds((const unsigned*)((const char*)(gbase) + (voff)[_i]), (PG8_LAS unsigned*)(lds + (bufoff) + ldsw + _i * 8192), 16, 0, 0); } while (0)
; #define PG8_LDA(dst, b, h) do { _Pragma("unroll") for (int m = 0; m < 4; ++m) _Pragma("unroll") for (int k = 0; k < 2; ++k) dst[m][k] = *(const PG8_LAS bf16x8*)(lds + PG8_SA(b, h) + aoff + m * 2048 + k * 1024); } while (0)
; #define PG8_MMA(ai, bj, At, Bt) do { __builtin_amdgcn_s_setprio(1); _Pragma("unroll") for (int m = 0; m < 4; ++m) _Pragma("unroll") for (int n = 0; n < 2; ++n) _Pragma("unroll") for (int k = 0; k < 2; ++k) \
;         acc[ai][bj][m][n] = __builtin_amdgcn_mfma_f32_16x16x32_bf16(Bt[n][k], At[m][k], acc[ai][bj][m][n], 0, 0, 0); __builtin_amdgcn_s_setprio(0); } while (0)
; #define PG8_WAIT_V(n) asm volatile("s_waitcnt vmcnt(" #n ")" ::: "memory")
; #define PG8_WAIT_L(n) asm volatile("s_waitcnt lgkmcnt(" #n ")" ::: "memory")
; #define PG8_BAR __builtin_amdgcn_s_barrier()
; #define PG8_SCHED __builtin_amdgcn_sched_barrier(0)
; template <class Epi, class Sched, bool ALIGN_EPI = false, bool SP2 = false>
; __device__ __forceinline__ void gemm_phase(PG8_LAS unsigned char* lds, const Gemm g, const Sched& S, const Epi& E) {
;     ...
;             PG8_LDA(At, 1, 1); PG8_STAGE(PG8_SB(1, 0), b3, voffB); PG8_STAGE(PG8_SB(1, 1), b3 + hstep, voffB); PG8_STAGE(PG8_SA(1, 0), a3, voffA);
;             PG8_WAIT_V(8); PG8_WAIT_L(0); PG8_BAR; PG8_MMA(1, 0, At, B0); PG8_MMA(1, 1, At, B1); PG8_BAR; PG8_SCHED;
;     ...
;         if constexpr (ALIGN_EPI) { if (wr == 0) PG8_BAR; }
	s_setprio 0
	s_add_i32 s26, s51, s28
	v_lshl_add_u64 v[162:163], v[162:163], 0, s[18:19]
	s_mov_b32 m0, s26
	ds_read_b128 v[180:183], v215 offset:49152
	ds_read_b128 v[184:187], v215 offset:50176
	ds_read_b128 v[188:191], v215 offset:51200
	ds_read_b128 v[192:195], v215 offset:52224
	ds_read_b128 v[196:199], v215 offset:53248
	ds_read_b128 v[200:203], v215 offset:54272
	ds_read_b128 v[204:207], v215 offset:55296
	ds_read_b128 v[220:223], v215 offset:56320
	global_load_lds_dwordx4 v[162:163], off
	s_add_i32 m0, s26, 0x2000
	s_add_u32 s10, s10, 0xb0080
	v_lshl_add_u64 v[162:163], v[208:209], 0, s[18:19]
	s_addc_u32 s11, s11, 0
	s_add_i32 s26, s52, s28
	global_load_lds_dwordx4 v[162:163], off
	v_lshl_add_u64 v[162:163], s[10:11], 0, v[166:167]
	s_mov_b32 m0, s26
	s_nop 0
	global_load_lds_dwordx4 v[162:163], off
	v_lshl_add_u64 v[162:163], s[10:11], 0, v[170:171]
	s_add_i32 m0, s26, 0x2000
	s_nop 0
	global_load_lds_dwordx4 v[162:163], off
	v_lshl_add_u64 v[162:163], v[224:225], 0, s[18:19]
	s_mov_b32 m0, s37
	s_nop 0
	global_load_lds_dwordx4 v[162:163], off
	v_lshl_add_u64 v[162:163], v[226:227], 0, s[18:19]
	s_mov_b32 m0, s38
	s_nop 0
	global_load_lds_dwordx4 v[162:163], off
	s_waitcnt vmcnt(8)
	s_waitcnt lgkmcnt(0)
	s_setprio 1
	s_barrier
	v_mfma_f32_16x16x32_bf16 v[60:63], v[128:131], v[180:183], v[60:63]
	v_mfma_f32_16x16x32_bf16 v[56:59], v[136:139], v[180:183], v[56:59]
	v_mfma_f32_16x16x32_bf16 v[44:47], v[128:131], v[188:191], v[44:47]
	v_mfma_f32_16x16x32_bf16 v[40:43], v[136:139], v[188:191], v[40:43]
	v_mfma_f32_16x16x32_bf16 v[28:31], v[128:131], v[196:199], v[28:31]
	v_mfma_f32_16x16x32_bf16 v[24:27], v[136:139], v[196:199], v[24:27]
	v_mfma_f32_16x16x32_bf16 v[12:15], v[128:131], v[204:207], v[12:15]
	v_mfma_f32_16x16x32_bf16 v[8:11], v[136:139], v[204:207], v[8:11]
	v_mfma_f32_16x16x32_bf16 v[60:63], v[132:135], v[184:187], v[60:63]
	v_mfma_f32_16x16x32_bf16 v[56:59], v[140:143], v[184:187], v[56:59]
	v_mfma_f32_16x16x32_bf16 v[44:47], v[132:135], v[192:195], v[44:47]
	v_mfma_f32_16x16x32_bf16 v[40:43], v[140:143], v[192:195], v[40:43]
	v_mfma_f32_16x16x32_bf16 v[28:31], v[132:135], v[200:203], v[28:31]
	v_mfma_f32_16x16x32_bf16 v[24:27], v[140:143], v[200:203], v[24:27]
	v_mfma_f32_16x16x32_bf16 v[12:15], v[132:135], v[220:223], v[12:15]
	v_mfma_f32_16x16x32_bf16 v[8:11], v[140:143], v[220:223], v[8:11]
	s_setprio 0
	s_setprio 1
	v_mfma_f32_16x16x32_bf16 v[52:55], v[144:147], v[180:183], v[52:55]
	v_mfma_f32_16x16x32_bf16 v[48:51], v[172:175], v[180:183], v[48:51]
	v_mfma_f32_16x16x32_bf16 v[36:39], v[144:147], v[188:191], v[36:39]
	v_mfma_f32_16x16x32_bf16 v[32:35], v[172:175], v[188:191], v[32:35]
	v_mfma_f32_16x16x32_bf16 v[20:23], v[144:147], v[196:199], v[20:23]
	v_mfma_f32_16x16x32_bf16 v[16:19], v[172:175], v[196:199], v[16:19]
	v_mfma_f32_16x16x32_bf16 v[4:7], v[144:147], v[204:207], v[4:7]
	v_mfma_f32_16x16x32_bf16 v[0:3], v[172:175], v[204:207], v[0:3]
	v_mfma_f32_16x16x32_bf16 v[52:55], v[148:151], v[184:187], v[52:55]
	v_mfma_f32_16x16x32_bf16 v[48:51], v[176:179], v[184:187], v[48:51]
	v_mfma_f32_16x16x32_bf16 v[36:39], v[148:151], v[192:195], v[36:39]
	v_mfma_f32_16x16x32_bf16 v[32:35], v[176:179], v[192:195], v[32:35]
	v_mfma_f32_16x16x32_bf16 v[20:23], v[148:151], v[200:203], v[20:23]
	v_mfma_f32_16x16x32_bf16 v[16:19], v[176:179], v[200:203], v[16:19]
	v_mfma_f32_16x16x32_bf16 v[4:7], v[148:151], v[220:223], v[4:7]
	v_mfma_f32_16x16x32_bf16 v[0:3], v[176:179], v[220:223], v[0:3]
	s_barrier
	s_setprio 0
	s_add_i32 s50, s50, 2
	s_add_u32 s6, s6, 0x100
	s_addc_u32 s7, s7, 0
	s_add_u32 s48, s48, 0x100
	s_addc_u32 s49, s49, 0
	s_cmp_gt_u32 s50, 41
	s_cbranch_scc0 .LBB0_1442
	s_and_b64 vcc, exec, s[20:21]
	s_cbranch_vccz .LBB0_1445
	s_barrier
